# K-loop waits: keep the original tile-to-tile transition (vmcnt(6) in a tile's last iteration, no phase-1/2 wait in the first) so a new tile's first phases do not wait for the previous epilogue's store
# baseline (speedup 1.0000x reference)
.LBB0_133:
	s_add_u32 s28, s22, 0x100
	s_addc_u32 s29, s23, 0
	s_add_i32 s85, 0, 0x10000
	v_add_u32_e32 v148, s85, v157
	ds_read_b128 v[130:133], v148
	ds_read_b128 v[134:137], v148 offset:1024
	ds_read_b128 v[138:141], v148 offset:2048
	ds_read_b128 v[148:151], v148 offset:3072
	s_cmp_eq_u32 s84, 40
	s_cselect_b32 s43, s17, s29
	s_cselect_b32 s42, s16, s28
	s_cselect_b32 s41, s19, s79
	s_cselect_b32 s40, s18, s34
	v_lshl_add_u64 v[188:189], s[22:23], 0, v[146:147]
	s_add_i32 m0, s54, 0xc000
	ds_read_b128 v[152:155], v159
	ds_read_b128 v[160:163], v159 offset:1024
	ds_read_b128 v[164:167], v159 offset:2048
	ds_read_b128 v[168:171], v159 offset:3072
	ds_read_b128 v[172:175], v159 offset:4096
	ds_read_b128 v[176:179], v159 offset:5120
	ds_read_b128 v[180:183], v159 offset:6144
	ds_read_b128 v[184:187], v159 offset:7168
	global_load_lds_dwordx4 v[188:189], off
	v_lshl_add_u64 v[188:189], s[22:23], 0, v[144:145]
	s_add_i32 m0, s54, 0xe000
	s_nop 0
	global_load_lds_dwordx4 v[188:189], off
	s_waitcnt lgkmcnt(8)
	s_cmp_eq_u32 s84, -2
	s_cbranch_scc1 .Lvw_0_1
	s_waitcnt vmcnt(10)
.Lvw_0_1:
	s_barrier
	s_waitcnt lgkmcnt(0)
	s_waitcnt lgkmcnt(0)
	v_mfma_f32_16x16x32_bf16 v[126:129], v[130:133], v[152:155], v[126:129]
	v_mfma_f32_16x16x32_bf16 v[122:125], v[138:141], v[152:155], v[122:125]
	v_mfma_f32_16x16x32_bf16 v[118:121], v[130:133], v[164:167], v[118:121]
	v_mfma_f32_16x16x32_bf16 v[106:109], v[138:141], v[164:167], v[106:109]
	v_mfma_f32_16x16x32_bf16 v[102:105], v[130:133], v[172:175], v[102:105]
	v_mfma_f32_16x16x32_bf16 v[90:93], v[138:141], v[172:175], v[90:93]
	v_mfma_f32_16x16x32_bf16 v[86:89], v[130:133], v[180:183], v[86:89]
	v_mfma_f32_16x16x32_bf16 v[74:77], v[138:141], v[180:183], v[74:77]
	v_mfma_f32_16x16x32_bf16 v[126:129], v[134:137], v[160:163], v[126:129]
	v_mfma_f32_16x16x32_bf16 v[122:125], v[148:151], v[160:163], v[122:125]
	v_mfma_f32_16x16x32_bf16 v[118:121], v[134:137], v[168:171], v[118:121]
	v_mfma_f32_16x16x32_bf16 v[106:109], v[148:151], v[168:171], v[106:109]
	v_mfma_f32_16x16x32_bf16 v[102:105], v[134:137], v[176:179], v[102:105]
	v_mfma_f32_16x16x32_bf16 v[90:93], v[148:151], v[176:179], v[90:93]
	v_mfma_f32_16x16x32_bf16 v[86:89], v[134:137], v[184:187], v[86:89]
	v_mfma_f32_16x16x32_bf16 v[74:77], v[148:151], v[184:187], v[74:77]
	s_barrier
	s_add_i32 s86, 0, 0x14000
	v_add_u32_e32 v196, s86, v157
	s_add_i32 s22, s85, s50
	ds_read_b128 v[188:191], v196
	ds_read_b128 v[192:195], v196 offset:1024
	ds_read_b128 v[208:211], v196 offset:2048
	ds_read_b128 v[212:215], v196 offset:3072
	v_lshl_add_u64 v[196:197], s[40:41], 0, v[16:17]
	s_mov_b32 m0, s22
	v_lshl_add_u64 v[216:217], s[40:41], 0, v[142:143]
	global_load_lds_dwordx4 v[196:197], off
	s_add_i32 m0, s22, 0x2000
	s_nop 0
	global_load_lds_dwordx4 v[216:217], off
	s_cmp_eq_u32 s84, -2
	s_cbranch_scc1 .Lvw_0_2
	s_waitcnt vmcnt(10)
.Lvw_0_2:
	s_barrier
	s_waitcnt lgkmcnt(0)
	s_waitcnt lgkmcnt(0)
	v_mfma_f32_16x16x32_bf16 v[114:117], v[188:191], v[152:155], v[114:117]
	v_mfma_f32_16x16x32_bf16 v[110:113], v[208:211], v[152:155], v[110:113]
	v_mfma_f32_16x16x32_bf16 v[98:101], v[188:191], v[164:167], v[98:101]
	v_mfma_f32_16x16x32_bf16 v[94:97], v[208:211], v[164:167], v[94:97]
	v_mfma_f32_16x16x32_bf16 v[82:85], v[188:191], v[172:175], v[82:85]
	v_mfma_f32_16x16x32_bf16 v[78:81], v[208:211], v[172:175], v[78:81]
	v_mfma_f32_16x16x32_bf16 v[70:73], v[188:191], v[180:183], v[70:73]
	v_mfma_f32_16x16x32_bf16 v[66:69], v[208:211], v[180:183], v[66:69]
	v_mfma_f32_16x16x32_bf16 v[114:117], v[192:195], v[160:163], v[114:117]
	v_mfma_f32_16x16x32_bf16 v[110:113], v[212:215], v[160:163], v[110:113]
	v_mfma_f32_16x16x32_bf16 v[98:101], v[192:195], v[168:171], v[98:101]
	v_mfma_f32_16x16x32_bf16 v[94:97], v[212:215], v[168:171], v[94:97]
	v_mfma_f32_16x16x32_bf16 v[82:85], v[192:195], v[176:179], v[82:85]
	v_mfma_f32_16x16x32_bf16 v[78:81], v[212:215], v[176:179], v[78:81]
	v_mfma_f32_16x16x32_bf16 v[70:73], v[192:195], v[184:187], v[70:73]
	v_mfma_f32_16x16x32_bf16 v[66:69], v[212:215], v[184:187], v[66:69]
	s_mov_b32 m0, s54
	v_lshl_add_u64 v[218:219], s[42:43], 0, v[16:17]
	s_barrier
	ds_read_b128 v[152:155], v159 offset:16384
	ds_read_b128 v[160:163], v159 offset:17408
	ds_read_b128 v[164:167], v159 offset:18432
	ds_read_b128 v[168:171], v159 offset:19456
	ds_read_b128 v[172:175], v159 offset:20480
	ds_read_b128 v[176:179], v159 offset:21504
	ds_read_b128 v[180:183], v159 offset:22528
	ds_read_b128 v[184:187], v159 offset:23552
	global_load_lds_dwordx4 v[218:219], off
	v_lshl_add_u64 v[220:221], s[42:43], 0, v[142:143]
	s_mov_b32 m0, s55
	s_nop 0
	global_load_lds_dwordx4 v[220:221], off
	s_barrier
	s_waitcnt lgkmcnt(0)
	s_waitcnt lgkmcnt(0)
	v_mfma_f32_16x16x32_bf16 v[62:65], v[130:133], v[152:155], v[62:65]
	v_mfma_f32_16x16x32_bf16 v[58:61], v[138:141], v[152:155], v[58:61]
	v_mfma_f32_16x16x32_bf16 v[54:57], v[130:133], v[164:167], v[54:57]
	v_mfma_f32_16x16x32_bf16 v[50:53], v[138:141], v[164:167], v[50:53]
	v_mfma_f32_16x16x32_bf16 v[46:49], v[130:133], v[172:175], v[46:49]
	v_mfma_f32_16x16x32_bf16 v[38:41], v[138:141], v[172:175], v[38:41]
	v_mfma_f32_16x16x32_bf16 v[30:33], v[130:133], v[180:183], v[30:33]
	v_mfma_f32_16x16x32_bf16 v[18:21], v[138:141], v[180:183], v[18:21]
	v_mfma_f32_16x16x32_bf16 v[62:65], v[134:137], v[160:163], v[62:65]
	v_mfma_f32_16x16x32_bf16 v[58:61], v[148:151], v[160:163], v[58:61]
	v_mfma_f32_16x16x32_bf16 v[54:57], v[134:137], v[168:171], v[54:57]
	v_mfma_f32_16x16x32_bf16 v[50:53], v[148:151], v[168:171], v[50:53]
	v_mfma_f32_16x16x32_bf16 v[46:49], v[134:137], v[176:179], v[46:49]
	v_mfma_f32_16x16x32_bf16 v[38:41], v[148:151], v[176:179], v[38:41]
	v_mfma_f32_16x16x32_bf16 v[30:33], v[134:137], v[184:187], v[30:33]
	v_mfma_f32_16x16x32_bf16 v[18:21], v[148:151], v[184:187], v[18:21]
	s_barrier
	s_add_u32 s22, s40, 0xb0000
	s_addc_u32 s23, s41, 0
	s_add_i32 s85, s86, s50
	v_lshl_add_u64 v[130:131], s[22:23], 0, v[16:17]
	s_mov_b32 m0, s85
	s_nop 0
	global_load_lds_dwordx4 v[130:131], off
	v_lshl_add_u64 v[130:131], s[22:23], 0, v[142:143]
	s_add_i32 m0, s85, 0x2000
	s_nop 0
	global_load_lds_dwordx4 v[130:131], off
	s_waitcnt vmcnt(10)
	s_barrier
	v_mfma_f32_16x16x32_bf16 v[42:45], v[188:191], v[152:155], v[42:45]
	v_mfma_f32_16x16x32_bf16 v[34:37], v[208:211], v[152:155], v[34:37]
	v_mfma_f32_16x16x32_bf16 v[26:29], v[188:191], v[164:167], v[26:29]
	v_mfma_f32_16x16x32_bf16 v[22:25], v[208:211], v[164:167], v[22:25]
	v_mfma_f32_16x16x32_bf16 v[12:15], v[188:191], v[172:175], v[12:15]
	v_mfma_f32_16x16x32_bf16 v[8:11], v[208:211], v[172:175], v[8:11]
	v_mfma_f32_16x16x32_bf16 v[4:7], v[188:191], v[180:183], v[4:7]
	v_mfma_f32_16x16x32_bf16 v[0:3], v[208:211], v[180:183], v[0:3]
	v_mfma_f32_16x16x32_bf16 v[42:45], v[192:195], v[160:163], v[42:45]
	v_mfma_f32_16x16x32_bf16 v[34:37], v[212:215], v[160:163], v[34:37]
	v_mfma_f32_16x16x32_bf16 v[26:29], v[192:195], v[168:171], v[26:29]
	v_mfma_f32_16x16x32_bf16 v[22:25], v[212:215], v[168:171], v[22:25]
	v_mfma_f32_16x16x32_bf16 v[12:15], v[192:195], v[176:179], v[12:15]
	v_mfma_f32_16x16x32_bf16 v[8:11], v[212:215], v[176:179], v[8:11]
	v_mfma_f32_16x16x32_bf16 v[4:7], v[192:195], v[184:187], v[4:7]
	v_mfma_f32_16x16x32_bf16 v[0:3], v[212:215], v[184:187], v[0:3]
	s_add_i32 s85, 0, 0x18000
	v_add_u32_e32 v148, s85, v157
	s_barrier
	ds_read_b128 v[130:133], v148
	ds_read_b128 v[134:137], v148 offset:1024
	ds_read_b128 v[138:141], v148 offset:2048
	ds_read_b128 v[148:151], v148 offset:3072
	s_add_u32 s22, s42, 0xb0000
	s_addc_u32 s23, s43, 0
	s_mov_b32 m0, s56
	v_lshl_add_u64 v[188:189], s[22:23], 0, v[16:17]
	ds_read_b128 v[152:155], v159 offset:32768
	ds_read_b128 v[160:163], v159 offset:33792
	ds_read_b128 v[164:167], v159 offset:34816
	ds_read_b128 v[168:171], v159 offset:35840
	ds_read_b128 v[172:175], v159 offset:36864
	ds_read_b128 v[176:179], v159 offset:37888
	ds_read_b128 v[180:183], v159 offset:38912
	ds_read_b128 v[184:187], v159 offset:39936
	global_load_lds_dwordx4 v[188:189], off
	v_lshl_add_u64 v[188:189], s[22:23], 0, v[142:143]
	s_mov_b32 m0, s57
	s_nop 0
	global_load_lds_dwordx4 v[188:189], off
	s_waitcnt lgkmcnt(8)
	s_waitcnt vmcnt(10)
	s_barrier
	s_waitcnt lgkmcnt(0)
	s_waitcnt lgkmcnt(0)
	v_mfma_f32_16x16x32_bf16 v[126:129], v[130:133], v[152:155], v[126:129]
	v_mfma_f32_16x16x32_bf16 v[122:125], v[138:141], v[152:155], v[122:125]
	v_mfma_f32_16x16x32_bf16 v[118:121], v[130:133], v[164:167], v[118:121]
	v_mfma_f32_16x16x32_bf16 v[106:109], v[138:141], v[164:167], v[106:109]
	v_mfma_f32_16x16x32_bf16 v[102:105], v[130:133], v[172:175], v[102:105]
	v_mfma_f32_16x16x32_bf16 v[90:93], v[138:141], v[172:175], v[90:93]
	v_mfma_f32_16x16x32_bf16 v[86:89], v[130:133], v[180:183], v[86:89]
	v_mfma_f32_16x16x32_bf16 v[74:77], v[138:141], v[180:183], v[74:77]
	v_mfma_f32_16x16x32_bf16 v[126:129], v[134:137], v[160:163], v[126:129]
	v_mfma_f32_16x16x32_bf16 v[122:125], v[148:151], v[160:163], v[122:125]
	v_mfma_f32_16x16x32_bf16 v[118:121], v[134:137], v[168:171], v[118:121]
	v_mfma_f32_16x16x32_bf16 v[106:109], v[148:151], v[168:171], v[106:109]
	v_mfma_f32_16x16x32_bf16 v[102:105], v[134:137], v[176:179], v[102:105]
	v_mfma_f32_16x16x32_bf16 v[90:93], v[148:151], v[176:179], v[90:93]
	v_mfma_f32_16x16x32_bf16 v[86:89], v[134:137], v[184:187], v[86:89]
	v_mfma_f32_16x16x32_bf16 v[74:77], v[148:151], v[184:187], v[74:77]
	s_barrier
	s_add_i32 s42, 0, 0x1c000
	s_add_i32 s22, s85, s50
	v_add_u32_e32 v212, s42, v157
	v_lshl_add_u64 v[196:197], v[196:197], 0, s[10:11]
	s_mov_b32 m0, s22
	ds_read_b128 v[188:191], v212
	ds_read_b128 v[192:195], v212 offset:1024
	ds_read_b128 v[208:211], v212 offset:2048
	ds_read_b128 v[212:215], v212 offset:3072
	global_load_lds_dwordx4 v[196:197], off
	v_lshl_add_u64 v[196:197], v[216:217], 0, s[10:11]
	s_add_i32 m0, s22, 0x2000
	s_nop 0
	global_load_lds_dwordx4 v[196:197], off
	s_waitcnt vmcnt(10)
	s_barrier
	s_waitcnt lgkmcnt(0)
	s_waitcnt lgkmcnt(0)
	v_mfma_f32_16x16x32_bf16 v[114:117], v[188:191], v[152:155], v[114:117]
	v_mfma_f32_16x16x32_bf16 v[110:113], v[208:211], v[152:155], v[110:113]
	v_mfma_f32_16x16x32_bf16 v[98:101], v[188:191], v[164:167], v[98:101]
	v_mfma_f32_16x16x32_bf16 v[94:97], v[208:211], v[164:167], v[94:97]
	v_mfma_f32_16x16x32_bf16 v[82:85], v[188:191], v[172:175], v[82:85]
	v_mfma_f32_16x16x32_bf16 v[78:81], v[208:211], v[172:175], v[78:81]
	v_mfma_f32_16x16x32_bf16 v[70:73], v[188:191], v[180:183], v[70:73]
	v_mfma_f32_16x16x32_bf16 v[66:69], v[208:211], v[180:183], v[66:69]
	v_mfma_f32_16x16x32_bf16 v[114:117], v[192:195], v[160:163], v[114:117]
	v_mfma_f32_16x16x32_bf16 v[110:113], v[212:215], v[160:163], v[110:113]
	v_mfma_f32_16x16x32_bf16 v[98:101], v[192:195], v[168:171], v[98:101]
	v_mfma_f32_16x16x32_bf16 v[94:97], v[212:215], v[168:171], v[94:97]
	v_mfma_f32_16x16x32_bf16 v[82:85], v[192:195], v[176:179], v[82:85]
	v_mfma_f32_16x16x32_bf16 v[78:81], v[212:215], v[176:179], v[78:81]
	v_mfma_f32_16x16x32_bf16 v[70:73], v[192:195], v[184:187], v[70:73]
	v_mfma_f32_16x16x32_bf16 v[66:69], v[212:215], v[184:187], v[66:69]
	s_mov_b32 m0, s58
	v_lshl_add_u64 v[196:197], v[218:219], 0, s[10:11]
	s_barrier
	ds_read_b128 v[152:155], v159 offset:49152
	ds_read_b128 v[160:163], v159 offset:50176
	ds_read_b128 v[164:167], v159 offset:51200
	ds_read_b128 v[168:171], v159 offset:52224
	ds_read_b128 v[172:175], v159 offset:53248
	ds_read_b128 v[176:179], v159 offset:54272
	ds_read_b128 v[180:183], v159 offset:55296
	ds_read_b128 v[184:187], v159 offset:56320
	global_load_lds_dwordx4 v[196:197], off
	v_lshl_add_u64 v[196:197], v[220:221], 0, s[10:11]
	s_mov_b32 m0, s59
	s_nop 0
	global_load_lds_dwordx4 v[196:197], off
	s_barrier
	s_waitcnt lgkmcnt(0)
	s_waitcnt lgkmcnt(0)
	v_mfma_f32_16x16x32_bf16 v[62:65], v[130:133], v[152:155], v[62:65]
	v_mfma_f32_16x16x32_bf16 v[58:61], v[138:141], v[152:155], v[58:61]
	v_mfma_f32_16x16x32_bf16 v[54:57], v[130:133], v[164:167], v[54:57]
	v_mfma_f32_16x16x32_bf16 v[50:53], v[138:141], v[164:167], v[50:53]
	v_mfma_f32_16x16x32_bf16 v[46:49], v[130:133], v[172:175], v[46:49]
	v_mfma_f32_16x16x32_bf16 v[38:41], v[138:141], v[172:175], v[38:41]
	v_mfma_f32_16x16x32_bf16 v[30:33], v[130:133], v[180:183], v[30:33]
	v_mfma_f32_16x16x32_bf16 v[18:21], v[138:141], v[180:183], v[18:21]
	v_mfma_f32_16x16x32_bf16 v[62:65], v[134:137], v[160:163], v[62:65]
	v_mfma_f32_16x16x32_bf16 v[58:61], v[148:151], v[160:163], v[58:61]
	v_mfma_f32_16x16x32_bf16 v[54:57], v[134:137], v[168:171], v[54:57]
	v_mfma_f32_16x16x32_bf16 v[50:53], v[148:151], v[168:171], v[50:53]
	v_mfma_f32_16x16x32_bf16 v[46:49], v[134:137], v[176:179], v[46:49]
	v_mfma_f32_16x16x32_bf16 v[38:41], v[148:151], v[176:179], v[38:41]
	v_mfma_f32_16x16x32_bf16 v[30:33], v[134:137], v[184:187], v[30:33]
	v_mfma_f32_16x16x32_bf16 v[18:21], v[148:151], v[184:187], v[18:21]
	s_barrier
	s_add_u32 s22, s40, 0xb0080
	s_addc_u32 s23, s41, 0
	s_add_i32 s40, s42, s50
	v_lshl_add_u64 v[130:131], s[22:23], 0, v[16:17]
	s_mov_b32 m0, s40
	s_nop 0
	global_load_lds_dwordx4 v[130:131], off
	v_lshl_add_u64 v[130:131], s[22:23], 0, v[142:143]
	s_add_i32 m0, s40, 0x2000
	s_nop 0
	global_load_lds_dwordx4 v[130:131], off
	s_cmp_eq_u32 s84, 40
	s_cbranch_scc0 .Lvl_0
	s_waitcnt vmcnt(6)
.Lvl_0:
	s_waitcnt vmcnt(10)
	s_barrier
	v_mfma_f32_16x16x32_bf16 v[42:45], v[188:191], v[152:155], v[42:45]
	v_mfma_f32_16x16x32_bf16 v[34:37], v[208:211], v[152:155], v[34:37]
	v_mfma_f32_16x16x32_bf16 v[26:29], v[188:191], v[164:167], v[26:29]
	v_mfma_f32_16x16x32_bf16 v[22:25], v[208:211], v[164:167], v[22:25]
	v_mfma_f32_16x16x32_bf16 v[12:15], v[188:191], v[172:175], v[12:15]
	v_mfma_f32_16x16x32_bf16 v[8:11], v[208:211], v[172:175], v[8:11]
	v_mfma_f32_16x16x32_bf16 v[4:7], v[188:191], v[180:183], v[4:7]
	v_mfma_f32_16x16x32_bf16 v[0:3], v[208:211], v[180:183], v[0:3]
	v_mfma_f32_16x16x32_bf16 v[42:45], v[192:195], v[160:163], v[42:45]
	v_mfma_f32_16x16x32_bf16 v[34:37], v[212:215], v[160:163], v[34:37]
	v_mfma_f32_16x16x32_bf16 v[26:29], v[192:195], v[168:171], v[26:29]
	v_mfma_f32_16x16x32_bf16 v[22:25], v[212:215], v[168:171], v[22:25]
	v_mfma_f32_16x16x32_bf16 v[12:15], v[192:195], v[176:179], v[12:15]
	v_mfma_f32_16x16x32_bf16 v[8:11], v[212:215], v[176:179], v[8:11]
	v_mfma_f32_16x16x32_bf16 v[4:7], v[192:195], v[184:187], v[4:7]
	v_mfma_f32_16x16x32_bf16 v[0:3], v[212:215], v[184:187], v[0:3]
	s_add_i32 s84, s84, 2
	s_add_u32 s34, s34, 0x100
	s_addc_u32 s79, s79, 0
	s_cmp_gt_u32 s84, 41
	s_mov_b64 s[22:23], s[28:29]
	s_barrier
	s_cbranch_scc0 .LBB0_133
	v_lshl_or_b32 v132, s12, 8, v158
	v_lshl_add_u32 v130, s2, 8, v156
	v_ashrrev_i32_e32 v133, 31, v132
	v_lshlrev_b64 v[148:149], 2, v[132:133]
	v_ashrrev_i32_e32 v131, 31, v130
	v_lshlrev_b64 v[152:153], 12, v[130:131]
	v_lshl_add_u64 v[150:151], s[4:5], 0, v[148:149]
	v_lshl_add_u64 v[154:155], v[150:151], 0, v[152:153]
	s_mov_b64 s[22:23], 0x10000
	v_lshl_add_u64 v[196:197], v[154:155], 0, s[22:23]
	s_mov_b64 s[22:23], 0x20000
	v_lshl_add_u64 v[224:225], v[154:155], 0, s[22:23]
	s_mov_b64 s[22:23], 0x30000
	v_lshl_add_u64 v[226:227], v[154:155], 0, s[22:23]
	s_mov_b64 s[22:23], 0x80000
	v_lshl_add_u64 v[240:241], v[154:155], 0, s[22:23]
	s_mov_b64 s[22:23], 0x90000
	v_lshl_add_u64 v[242:243], v[154:155], 0, s[22:23]
	s_mov_b64 s[22:23], 0xa0000
	v_lshl_add_u64 v[244:245], v[154:155], 0, s[22:23]
	s_mov_b64 s[22:23], 0xb0000
	v_lshl_add_u64 v[246:247], v[154:155], 0, s[22:23]
	s_sub_u32 s100, s14, s4
	s_subb_u32 s101, s15, s5
	global_load_dwordx4 v[160:163], v[154:155], off
	global_load_dwordx4 v[164:167], v[154:155], off offset:64
	global_load_dwordx4 v[168:171], v[154:155], off offset:512
	global_load_dwordx4 v[172:175], v[154:155], off offset:576
	global_load_dwordx4 v[176:179], v[196:197], off
	global_load_dwordx4 v[180:183], v[196:197], off offset:64
	global_load_dwordx4 v[184:187], v[196:197], off offset:512
	global_load_dwordx4 v[188:191], v[196:197], off offset:576
	global_load_dwordx4 v[192:195], v[224:225], off
	global_load_dwordx4 v[208:211], v[224:225], off offset:64
	global_load_dwordx4 v[212:215], v[224:225], off offset:512
	global_load_dwordx4 v[216:219], v[224:225], off offset:576
	global_load_dwordx4 v[220:223], v[226:227], off
	global_load_dwordx4 v[138:141], v[226:227], off offset:64
	global_load_dwordx4 v[134:137], v[226:227], off offset:512
	global_load_dwordx4 v[130:133], v[226:227], off offset:576
	s_waitcnt vmcnt(12)
	v_pk_fma_f32 v[126:127], v[126:127], 0.5, v[160:161] op_sel_hi:[1,0,1]
	v_pk_fma_f32 v[128:129], v[128:129], 0.5, v[162:163] op_sel_hi:[1,0,1]
	v_pk_fma_f32 v[122:123], v[122:123], 0.5, v[164:165] op_sel_hi:[1,0,1]
	v_pk_fma_f32 v[124:125], v[124:125], 0.5, v[166:167] op_sel_hi:[1,0,1]
	v_pk_fma_f32 v[114:115], v[114:115], 0.5, v[168:169] op_sel_hi:[1,0,1]
	v_pk_fma_f32 v[116:117], v[116:117], 0.5, v[170:171] op_sel_hi:[1,0,1]
	v_pk_fma_f32 v[110:111], v[110:111], 0.5, v[172:173] op_sel_hi:[1,0,1]
	v_pk_fma_f32 v[112:113], v[112:113], 0.5, v[174:175] op_sel_hi:[1,0,1]
	s_waitcnt vmcnt(8)
	v_pk_fma_f32 v[118:119], v[118:119], 0.5, v[176:177] op_sel_hi:[1,0,1]
	v_pk_fma_f32 v[120:121], v[120:121], 0.5, v[178:179] op_sel_hi:[1,0,1]
	v_pk_fma_f32 v[106:107], v[106:107], 0.5, v[180:181] op_sel_hi:[1,0,1]
	v_pk_fma_f32 v[108:109], v[108:109], 0.5, v[182:183] op_sel_hi:[1,0,1]
	v_pk_fma_f32 v[98:99], v[98:99], 0.5, v[184:185] op_sel_hi:[1,0,1]
	v_pk_fma_f32 v[100:101], v[100:101], 0.5, v[186:187] op_sel_hi:[1,0,1]
	v_pk_fma_f32 v[94:95], v[94:95], 0.5, v[188:189] op_sel_hi:[1,0,1]
	v_pk_fma_f32 v[96:97], v[96:97], 0.5, v[190:191] op_sel_hi:[1,0,1]
	s_waitcnt vmcnt(4)
	v_pk_fma_f32 v[102:103], v[102:103], 0.5, v[192:193] op_sel_hi:[1,0,1]
	v_pk_fma_f32 v[104:105], v[104:105], 0.5, v[194:195] op_sel_hi:[1,0,1]
	v_pk_fma_f32 v[90:91], v[90:91], 0.5, v[208:209] op_sel_hi:[1,0,1]
	v_pk_fma_f32 v[92:93], v[92:93], 0.5, v[210:211] op_sel_hi:[1,0,1]
	v_pk_fma_f32 v[82:83], v[82:83], 0.5, v[212:213] op_sel_hi:[1,0,1]
	v_pk_fma_f32 v[84:85], v[84:85], 0.5, v[214:215] op_sel_hi:[1,0,1]
	v_pk_fma_f32 v[78:79], v[78:79], 0.5, v[216:217] op_sel_hi:[1,0,1]
	v_pk_fma_f32 v[80:81], v[80:81], 0.5, v[218:219] op_sel_hi:[1,0,1]
	s_waitcnt vmcnt(0)
	v_pk_fma_f32 v[86:87], v[86:87], 0.5, v[220:221] op_sel_hi:[1,0,1]
	v_pk_fma_f32 v[88:89], v[88:89], 0.5, v[222:223] op_sel_hi:[1,0,1]
	v_pk_fma_f32 v[74:75], v[74:75], 0.5, v[138:139] op_sel_hi:[1,0,1]
	v_pk_fma_f32 v[76:77], v[76:77], 0.5, v[140:141] op_sel_hi:[1,0,1]
	v_pk_fma_f32 v[70:71], v[70:71], 0.5, v[134:135] op_sel_hi:[1,0,1]
	v_pk_fma_f32 v[72:73], v[72:73], 0.5, v[136:137] op_sel_hi:[1,0,1]
	v_pk_fma_f32 v[66:67], v[66:67], 0.5, v[130:131] op_sel_hi:[1,0,1]
	v_pk_fma_f32 v[68:69], v[68:69], 0.5, v[132:133] op_sel_hi:[1,0,1]
	global_load_dwordx4 v[160:163], v[240:241], off
	global_load_dwordx4 v[164:167], v[240:241], off offset:64
	global_load_dwordx4 v[168:171], v[240:241], off offset:512
	global_load_dwordx4 v[172:175], v[240:241], off offset:576
	global_load_dwordx4 v[176:179], v[242:243], off
	global_load_dwordx4 v[180:183], v[242:243], off offset:64
	global_load_dwordx4 v[184:187], v[242:243], off offset:512
	global_load_dwordx4 v[188:191], v[242:243], off offset:576
	global_load_dwordx4 v[192:195], v[244:245], off
	global_load_dwordx4 v[208:211], v[244:245], off offset:64
	global_load_dwordx4 v[212:215], v[244:245], off offset:512
	global_load_dwordx4 v[216:219], v[244:245], off offset:576
	global_load_dwordx4 v[220:223], v[246:247], off
	global_load_dwordx4 v[138:141], v[246:247], off offset:64
	global_load_dwordx4 v[134:137], v[246:247], off offset:512
	global_load_dwordx4 v[130:133], v[246:247], off offset:576
	v_lshl_add_u64 v[154:155], v[154:155], 0, s[100:101]
	v_lshl_add_u64 v[196:197], v[196:197], 0, s[100:101]
	v_lshl_add_u64 v[224:225], v[224:225], 0, s[100:101]
	v_lshl_add_u64 v[226:227], v[226:227], 0, s[100:101]
	global_store_dwordx4 v[154:155], v[126:129], off
	global_store_dwordx4 v[154:155], v[122:125], off offset:64
	global_store_dwordx4 v[154:155], v[114:117], off offset:512
	global_store_dwordx4 v[154:155], v[110:113], off offset:576
	global_store_dwordx4 v[196:197], v[118:121], off
	global_store_dwordx4 v[196:197], v[106:109], off offset:64
	global_store_dwordx4 v[196:197], v[98:101], off offset:512
	global_store_dwordx4 v[196:197], v[94:97], off offset:576
	global_store_dwordx4 v[224:225], v[102:105], off
	global_store_dwordx4 v[224:225], v[90:93], off offset:64
	global_store_dwordx4 v[224:225], v[82:85], off offset:512
	global_store_dwordx4 v[224:225], v[78:81], off offset:576
	global_store_dwordx4 v[226:227], v[86:89], off
	global_store_dwordx4 v[226:227], v[74:77], off offset:64
	global_store_dwordx4 v[226:227], v[70:73], off offset:512
	global_store_dwordx4 v[226:227], v[66:69], off offset:576
	s_waitcnt vmcnt(0)
	v_pk_fma_f32 v[62:63], v[62:63], 0.5, v[160:161] op_sel_hi:[1,0,1]
	v_pk_fma_f32 v[64:65], v[64:65], 0.5, v[162:163] op_sel_hi:[1,0,1]
	v_pk_fma_f32 v[58:59], v[58:59], 0.5, v[164:165] op_sel_hi:[1,0,1]
	v_pk_fma_f32 v[60:61], v[60:61], 0.5, v[166:167] op_sel_hi:[1,0,1]
	v_pk_fma_f32 v[42:43], v[42:43], 0.5, v[168:169] op_sel_hi:[1,0,1]
	v_pk_fma_f32 v[44:45], v[44:45], 0.5, v[170:171] op_sel_hi:[1,0,1]
	v_pk_fma_f32 v[34:35], v[34:35], 0.5, v[172:173] op_sel_hi:[1,0,1]
	v_pk_fma_f32 v[36:37], v[36:37], 0.5, v[174:175] op_sel_hi:[1,0,1]
	v_pk_fma_f32 v[54:55], v[54:55], 0.5, v[176:177] op_sel_hi:[1,0,1]
	v_pk_fma_f32 v[56:57], v[56:57], 0.5, v[178:179] op_sel_hi:[1,0,1]
	v_pk_fma_f32 v[50:51], v[50:51], 0.5, v[180:181] op_sel_hi:[1,0,1]
	v_pk_fma_f32 v[52:53], v[52:53], 0.5, v[182:183] op_sel_hi:[1,0,1]
	v_pk_fma_f32 v[26:27], v[26:27], 0.5, v[184:185] op_sel_hi:[1,0,1]
	v_pk_fma_f32 v[28:29], v[28:29], 0.5, v[186:187] op_sel_hi:[1,0,1]
	v_pk_fma_f32 v[22:23], v[22:23], 0.5, v[188:189] op_sel_hi:[1,0,1]
	v_pk_fma_f32 v[24:25], v[24:25], 0.5, v[190:191] op_sel_hi:[1,0,1]
	v_pk_fma_f32 v[46:47], v[46:47], 0.5, v[192:193] op_sel_hi:[1,0,1]
	v_pk_fma_f32 v[48:49], v[48:49], 0.5, v[194:195] op_sel_hi:[1,0,1]
	v_pk_fma_f32 v[38:39], v[38:39], 0.5, v[208:209] op_sel_hi:[1,0,1]
	v_pk_fma_f32 v[40:41], v[40:41], 0.5, v[210:211] op_sel_hi:[1,0,1]
	v_pk_fma_f32 v[12:13], v[12:13], 0.5, v[212:213] op_sel_hi:[1,0,1]
	v_pk_fma_f32 v[14:15], v[14:15], 0.5, v[214:215] op_sel_hi:[1,0,1]
	v_pk_fma_f32 v[8:9], v[8:9], 0.5, v[216:217] op_sel_hi:[1,0,1]
	v_pk_fma_f32 v[10:11], v[10:11], 0.5, v[218:219] op_sel_hi:[1,0,1]
	v_pk_fma_f32 v[30:31], v[30:31], 0.5, v[220:221] op_sel_hi:[1,0,1]
	v_pk_fma_f32 v[32:33], v[32:33], 0.5, v[222:223] op_sel_hi:[1,0,1]
	v_pk_fma_f32 v[18:19], v[18:19], 0.5, v[138:139] op_sel_hi:[1,0,1]
	v_pk_fma_f32 v[20:21], v[20:21], 0.5, v[140:141] op_sel_hi:[1,0,1]
	v_pk_fma_f32 v[4:5], v[4:5], 0.5, v[134:135] op_sel_hi:[1,0,1]
	v_pk_fma_f32 v[6:7], v[6:7], 0.5, v[136:137] op_sel_hi:[1,0,1]
	v_pk_fma_f32 v[0:1], v[0:1], 0.5, v[130:131] op_sel_hi:[1,0,1]
	v_pk_fma_f32 v[2:3], v[2:3], 0.5, v[132:133] op_sel_hi:[1,0,1]
	v_lshl_add_u64 v[240:241], v[240:241], 0, s[100:101]
	v_lshl_add_u64 v[242:243], v[242:243], 0, s[100:101]
	v_lshl_add_u64 v[244:245], v[244:245], 0, s[100:101]
	v_lshl_add_u64 v[246:247], v[246:247], 0, s[100:101]
	global_store_dwordx4 v[240:241], v[62:65], off
	global_store_dwordx4 v[240:241], v[58:61], off offset:64
	global_store_dwordx4 v[240:241], v[42:45], off offset:512
	global_store_dwordx4 v[240:241], v[34:37], off offset:576
	global_store_dwordx4 v[242:243], v[54:57], off
	global_store_dwordx4 v[242:243], v[50:53], off offset:64
	global_store_dwordx4 v[242:243], v[26:29], off offset:512
	global_store_dwordx4 v[242:243], v[22:25], off offset:576
	global_store_dwordx4 v[244:245], v[46:49], off
	global_store_dwordx4 v[244:245], v[38:41], off offset:64
	global_store_dwordx4 v[244:245], v[12:15], off offset:512
	global_store_dwordx4 v[244:245], v[8:11], off offset:576
	global_store_dwordx4 v[246:247], v[30:33], off
	global_store_dwordx4 v[246:247], v[18:21], off offset:64
	global_store_dwordx4 v[246:247], v[4:7], off offset:512
	global_store_dwordx4 v[246:247], v[0:3], off offset:576
	s_and_b64 vcc, exec, s[38:39]
	s_mov_b32 s12, s82
	s_mov_b32 s2, s83
	s_mov_b64 s[28:29], s[18:19]
	s_mov_b64 s[22:23], s[16:17]
	s_mov_b32 s86, 0x38c0000
	s_cbranch_vccz .LBB0_122
	s_waitcnt vmcnt(0)
	s_cmpk_gt_u32 s48, 0xff
	s_cbranch_scc1 .LBB0_137
	s_barrier

.LBB0_147:
	s_add_u32 s18, s16, 0xfffc0080
	s_addc_u32 s19, s17, -1
	s_add_i32 s83, 0, 0x10000
	v_add_u32_e32 v140, s83, v143
	ds_read_b128 v[146:149], v140
	ds_read_b128 v[150:153], v140 offset:1024
	ds_read_b128 v[154:157], v140 offset:2048
	ds_read_b128 v[158:161], v140 offset:3072
	s_cmp_eq_u32 s82, 12
	s_cselect_b32 s23, s12, s19
	s_cselect_b32 s22, s29, s18
	s_cselect_b32 s19, s9, s79
	s_cselect_b32 s18, s34, s61
	v_lshl_add_u64 v[140:141], s[16:17], 0, v[138:139]
	s_add_i32 m0, s15, 0xc000
	ds_read_b128 v[162:165], v145
	ds_read_b128 v[166:169], v145 offset:1024
	ds_read_b128 v[170:173], v145 offset:2048
	ds_read_b128 v[174:177], v145 offset:3072
	ds_read_b128 v[178:181], v145 offset:4096
	ds_read_b128 v[182:185], v145 offset:5120
	ds_read_b128 v[186:189], v145 offset:6144
	ds_read_b128 v[190:193], v145 offset:7168
	global_load_lds_dwordx4 v[140:141], off
	v_lshl_add_u64 v[140:141], s[16:17], 0, v[136:137]
	s_add_i32 m0, s15, 0xe000
	s_nop 0
	global_load_lds_dwordx4 v[140:141], off
	s_waitcnt lgkmcnt(8)
	s_cmp_eq_u32 s82, -2
	s_cbranch_scc1 .Lvw_1_1
	s_waitcnt vmcnt(10)
.Lvw_1_1:
	s_barrier
	s_waitcnt lgkmcnt(0)
	s_waitcnt lgkmcnt(0)
	v_mfma_f32_16x16x32_bf16 v[126:129], v[146:149], v[162:165], v[126:129]
	v_mfma_f32_16x16x32_bf16 v[118:121], v[154:157], v[162:165], v[118:121]
	v_mfma_f32_16x16x32_bf16 v[110:113], v[146:149], v[170:173], v[110:113]
	v_mfma_f32_16x16x32_bf16 v[102:105], v[154:157], v[170:173], v[102:105]
	v_mfma_f32_16x16x32_bf16 v[94:97], v[146:149], v[178:181], v[94:97]
	v_mfma_f32_16x16x32_bf16 v[86:89], v[154:157], v[178:181], v[86:89]
	v_mfma_f32_16x16x32_bf16 v[78:81], v[146:149], v[186:189], v[78:81]
	v_mfma_f32_16x16x32_bf16 v[70:73], v[154:157], v[186:189], v[70:73]
	v_mfma_f32_16x16x32_bf16 v[126:129], v[150:153], v[166:169], v[126:129]
	v_mfma_f32_16x16x32_bf16 v[118:121], v[158:161], v[166:169], v[118:121]
	v_mfma_f32_16x16x32_bf16 v[110:113], v[150:153], v[174:177], v[110:113]
	v_mfma_f32_16x16x32_bf16 v[102:105], v[158:161], v[174:177], v[102:105]
	v_mfma_f32_16x16x32_bf16 v[94:97], v[150:153], v[182:185], v[94:97]
	v_mfma_f32_16x16x32_bf16 v[86:89], v[158:161], v[182:185], v[86:89]
	v_mfma_f32_16x16x32_bf16 v[78:81], v[150:153], v[190:193], v[78:81]
	v_mfma_f32_16x16x32_bf16 v[70:73], v[158:161], v[190:193], v[70:73]
	s_barrier
	s_add_i32 s86, 0, 0x14000
	v_add_u32_e32 v140, s86, v143
	s_add_i32 s83, s83, s51
	ds_read_b128 v[194:197], v140
	ds_read_b128 v[208:211], v140 offset:1024
	ds_read_b128 v[212:215], v140 offset:2048
	ds_read_b128 v[216:219], v140 offset:3072
	v_lshl_add_u64 v[140:141], s[18:19], 0, v[16:17]
	s_mov_b32 m0, s83
	v_lshl_add_u64 v[220:221], s[18:19], 0, v[130:131]
	global_load_lds_dwordx4 v[140:141], off
	s_add_i32 m0, s83, 0x2000
	s_nop 0
	global_load_lds_dwordx4 v[220:221], off
	s_cmp_eq_u32 s82, -2
	s_cbranch_scc1 .Lvw_1_2
	s_waitcnt vmcnt(10)
.Lvw_1_2:
	s_barrier
	s_waitcnt lgkmcnt(0)
	s_waitcnt lgkmcnt(0)
	v_mfma_f32_16x16x32_bf16 v[122:125], v[194:197], v[162:165], v[122:125]
	v_mfma_f32_16x16x32_bf16 v[114:117], v[212:215], v[162:165], v[114:117]
	v_mfma_f32_16x16x32_bf16 v[106:109], v[194:197], v[170:173], v[106:109]
	v_mfma_f32_16x16x32_bf16 v[98:101], v[212:215], v[170:173], v[98:101]
	v_mfma_f32_16x16x32_bf16 v[90:93], v[194:197], v[178:181], v[90:93]
	v_mfma_f32_16x16x32_bf16 v[82:85], v[212:215], v[178:181], v[82:85]
	v_mfma_f32_16x16x32_bf16 v[74:77], v[194:197], v[186:189], v[74:77]
	v_mfma_f32_16x16x32_bf16 v[66:69], v[212:215], v[186:189], v[66:69]
	v_mfma_f32_16x16x32_bf16 v[122:125], v[208:211], v[166:169], v[122:125]
	v_mfma_f32_16x16x32_bf16 v[114:117], v[216:219], v[166:169], v[114:117]
	v_mfma_f32_16x16x32_bf16 v[106:109], v[208:211], v[174:177], v[106:109]
	v_mfma_f32_16x16x32_bf16 v[98:101], v[216:219], v[174:177], v[98:101]
	v_mfma_f32_16x16x32_bf16 v[90:93], v[208:211], v[182:185], v[90:93]
	v_mfma_f32_16x16x32_bf16 v[82:85], v[216:219], v[182:185], v[82:85]
	v_mfma_f32_16x16x32_bf16 v[74:77], v[208:211], v[190:193], v[74:77]
	v_mfma_f32_16x16x32_bf16 v[66:69], v[216:219], v[190:193], v[66:69]
	s_mov_b32 m0, s15
	v_lshl_add_u64 v[222:223], s[22:23], 0, v[134:135]
	s_barrier
	ds_read_b128 v[162:165], v145 offset:16384
	ds_read_b128 v[166:169], v145 offset:17408
	ds_read_b128 v[170:173], v145 offset:18432
	ds_read_b128 v[174:177], v145 offset:19456
	ds_read_b128 v[178:181], v145 offset:20480
	ds_read_b128 v[182:185], v145 offset:21504
	ds_read_b128 v[186:189], v145 offset:22528
	ds_read_b128 v[190:193], v145 offset:23552
	global_load_lds_dwordx4 v[222:223], off
	v_lshl_add_u64 v[224:225], s[22:23], 0, v[132:133]
	s_mov_b32 m0, s54
	s_nop 0
	global_load_lds_dwordx4 v[224:225], off
	s_barrier
	s_waitcnt lgkmcnt(0)
	s_waitcnt lgkmcnt(0)
	v_mfma_f32_16x16x32_bf16 v[62:65], v[146:149], v[162:165], v[62:65]
	v_mfma_f32_16x16x32_bf16 v[54:57], v[154:157], v[162:165], v[54:57]
	v_mfma_f32_16x16x32_bf16 v[46:49], v[146:149], v[170:173], v[46:49]
	v_mfma_f32_16x16x32_bf16 v[38:41], v[154:157], v[170:173], v[38:41]
	v_mfma_f32_16x16x32_bf16 v[30:33], v[146:149], v[178:181], v[30:33]
	v_mfma_f32_16x16x32_bf16 v[22:25], v[154:157], v[178:181], v[22:25]
	v_mfma_f32_16x16x32_bf16 v[12:15], v[146:149], v[186:189], v[12:15]
	v_mfma_f32_16x16x32_bf16 v[4:7], v[154:157], v[186:189], v[4:7]
	v_mfma_f32_16x16x32_bf16 v[62:65], v[150:153], v[166:169], v[62:65]
	v_mfma_f32_16x16x32_bf16 v[54:57], v[158:161], v[166:169], v[54:57]
	v_mfma_f32_16x16x32_bf16 v[46:49], v[150:153], v[174:177], v[46:49]
	v_mfma_f32_16x16x32_bf16 v[38:41], v[158:161], v[174:177], v[38:41]
	v_mfma_f32_16x16x32_bf16 v[30:33], v[150:153], v[182:185], v[30:33]
	v_mfma_f32_16x16x32_bf16 v[22:25], v[158:161], v[182:185], v[22:25]
	v_mfma_f32_16x16x32_bf16 v[12:15], v[150:153], v[190:193], v[12:15]
	v_mfma_f32_16x16x32_bf16 v[4:7], v[158:161], v[190:193], v[4:7]
	s_barrier
	s_add_u32 s84, s18, 0x40000
	s_addc_u32 s85, s19, 0
	s_add_i32 s83, s86, s51
	v_lshl_add_u64 v[146:147], s[84:85], 0, v[16:17]
	s_mov_b32 m0, s83
	s_nop 0
	global_load_lds_dwordx4 v[146:147], off
	v_lshl_add_u64 v[146:147], s[84:85], 0, v[130:131]
	s_add_i32 m0, s83, 0x2000
	s_nop 0
	global_load_lds_dwordx4 v[146:147], off
	s_waitcnt vmcnt(10)
	s_barrier
	v_mfma_f32_16x16x32_bf16 v[58:61], v[194:197], v[162:165], v[58:61]
	v_mfma_f32_16x16x32_bf16 v[50:53], v[212:215], v[162:165], v[50:53]
	v_mfma_f32_16x16x32_bf16 v[42:45], v[194:197], v[170:173], v[42:45]
	v_mfma_f32_16x16x32_bf16 v[34:37], v[212:215], v[170:173], v[34:37]
	v_mfma_f32_16x16x32_bf16 v[26:29], v[194:197], v[178:181], v[26:29]
	v_mfma_f32_16x16x32_bf16 v[18:21], v[212:215], v[178:181], v[18:21]
	v_mfma_f32_16x16x32_bf16 v[8:11], v[194:197], v[186:189], v[8:11]
	v_mfma_f32_16x16x32_bf16 v[0:3], v[212:215], v[186:189], v[0:3]
	v_mfma_f32_16x16x32_bf16 v[58:61], v[208:211], v[166:169], v[58:61]
	v_mfma_f32_16x16x32_bf16 v[50:53], v[216:219], v[166:169], v[50:53]
	v_mfma_f32_16x16x32_bf16 v[42:45], v[208:211], v[174:177], v[42:45]
	v_mfma_f32_16x16x32_bf16 v[34:37], v[216:219], v[174:177], v[34:37]
	v_mfma_f32_16x16x32_bf16 v[26:29], v[208:211], v[182:185], v[26:29]
	v_mfma_f32_16x16x32_bf16 v[18:21], v[216:219], v[182:185], v[18:21]
	v_mfma_f32_16x16x32_bf16 v[8:11], v[208:211], v[190:193], v[8:11]
	v_mfma_f32_16x16x32_bf16 v[0:3], v[216:219], v[190:193], v[0:3]
	s_add_i32 s83, 0, 0x18000
	v_add_u32_e32 v158, s83, v143
	s_barrier
	ds_read_b128 v[146:149], v158
	ds_read_b128 v[150:153], v158 offset:1024
	ds_read_b128 v[154:157], v158 offset:2048
	ds_read_b128 v[158:161], v158 offset:3072
	s_add_u32 s22, s22, 0x40000
	s_addc_u32 s23, s23, 0
	s_mov_b32 m0, s55
	v_lshl_add_u64 v[194:195], s[22:23], 0, v[134:135]
	ds_read_b128 v[162:165], v145 offset:32768
	ds_read_b128 v[166:169], v145 offset:33792
	ds_read_b128 v[170:173], v145 offset:34816
	ds_read_b128 v[174:177], v145 offset:35840
	ds_read_b128 v[178:181], v145 offset:36864
	ds_read_b128 v[182:185], v145 offset:37888
	ds_read_b128 v[186:189], v145 offset:38912
	ds_read_b128 v[190:193], v145 offset:39936
	global_load_lds_dwordx4 v[194:195], off
	v_lshl_add_u64 v[194:195], s[22:23], 0, v[132:133]
	s_mov_b32 m0, s56
	s_nop 0
	global_load_lds_dwordx4 v[194:195], off
	s_waitcnt lgkmcnt(8)
	s_waitcnt vmcnt(10)
	s_barrier
	s_waitcnt lgkmcnt(0)
	s_waitcnt lgkmcnt(0)
	v_mfma_f32_16x16x32_bf16 v[126:129], v[146:149], v[162:165], v[126:129]
	v_mfma_f32_16x16x32_bf16 v[118:121], v[154:157], v[162:165], v[118:121]
	v_mfma_f32_16x16x32_bf16 v[110:113], v[146:149], v[170:173], v[110:113]
	v_mfma_f32_16x16x32_bf16 v[102:105], v[154:157], v[170:173], v[102:105]
	v_mfma_f32_16x16x32_bf16 v[94:97], v[146:149], v[178:181], v[94:97]
	v_mfma_f32_16x16x32_bf16 v[86:89], v[154:157], v[178:181], v[86:89]
	v_mfma_f32_16x16x32_bf16 v[78:81], v[146:149], v[186:189], v[78:81]
	v_mfma_f32_16x16x32_bf16 v[70:73], v[154:157], v[186:189], v[70:73]
	v_mfma_f32_16x16x32_bf16 v[126:129], v[150:153], v[166:169], v[126:129]
	v_mfma_f32_16x16x32_bf16 v[118:121], v[158:161], v[166:169], v[118:121]
	v_mfma_f32_16x16x32_bf16 v[110:113], v[150:153], v[174:177], v[110:113]
	v_mfma_f32_16x16x32_bf16 v[102:105], v[158:161], v[174:177], v[102:105]
	v_mfma_f32_16x16x32_bf16 v[94:97], v[150:153], v[182:185], v[94:97]
	v_mfma_f32_16x16x32_bf16 v[86:89], v[158:161], v[182:185], v[86:89]
	v_mfma_f32_16x16x32_bf16 v[78:81], v[150:153], v[190:193], v[78:81]
	v_mfma_f32_16x16x32_bf16 v[70:73], v[158:161], v[190:193], v[70:73]
	s_barrier
	s_add_i32 s22, 0, 0x1c000
	s_add_i32 s23, s83, s51
	v_add_u32_e32 v216, s22, v143
	v_lshl_add_u64 v[140:141], v[140:141], 0, s[10:11]
	s_mov_b32 m0, s23
	ds_read_b128 v[194:197], v216
	ds_read_b128 v[208:211], v216 offset:1024
	ds_read_b128 v[212:215], v216 offset:2048
	ds_read_b128 v[216:219], v216 offset:3072
	global_load_lds_dwordx4 v[140:141], off
	v_lshl_add_u64 v[140:141], v[220:221], 0, s[10:11]
	s_add_i32 m0, s23, 0x2000
	s_nop 0
	global_load_lds_dwordx4 v[140:141], off
	s_waitcnt vmcnt(10)
	s_barrier
	s_waitcnt lgkmcnt(0)
	s_waitcnt lgkmcnt(0)
	v_mfma_f32_16x16x32_bf16 v[122:125], v[194:197], v[162:165], v[122:125]
	v_mfma_f32_16x16x32_bf16 v[114:117], v[212:215], v[162:165], v[114:117]
	v_mfma_f32_16x16x32_bf16 v[106:109], v[194:197], v[170:173], v[106:109]
	v_mfma_f32_16x16x32_bf16 v[98:101], v[212:215], v[170:173], v[98:101]
	v_mfma_f32_16x16x32_bf16 v[90:93], v[194:197], v[178:181], v[90:93]
	v_mfma_f32_16x16x32_bf16 v[82:85], v[212:215], v[178:181], v[82:85]
	v_mfma_f32_16x16x32_bf16 v[74:77], v[194:197], v[186:189], v[74:77]
	v_mfma_f32_16x16x32_bf16 v[66:69], v[212:215], v[186:189], v[66:69]
	v_mfma_f32_16x16x32_bf16 v[122:125], v[208:211], v[166:169], v[122:125]
	v_mfma_f32_16x16x32_bf16 v[114:117], v[216:219], v[166:169], v[114:117]
	v_mfma_f32_16x16x32_bf16 v[106:109], v[208:211], v[174:177], v[106:109]
	v_mfma_f32_16x16x32_bf16 v[98:101], v[216:219], v[174:177], v[98:101]
	v_mfma_f32_16x16x32_bf16 v[90:93], v[208:211], v[182:185], v[90:93]
	v_mfma_f32_16x16x32_bf16 v[82:85], v[216:219], v[182:185], v[82:85]
	v_mfma_f32_16x16x32_bf16 v[74:77], v[208:211], v[190:193], v[74:77]
	v_mfma_f32_16x16x32_bf16 v[66:69], v[216:219], v[190:193], v[66:69]
	s_mov_b32 m0, s57
	v_lshl_add_u64 v[140:141], v[222:223], 0, s[10:11]
	s_barrier
	ds_read_b128 v[162:165], v145 offset:49152
	ds_read_b128 v[166:169], v145 offset:50176
	ds_read_b128 v[170:173], v145 offset:51200
	ds_read_b128 v[174:177], v145 offset:52224
	ds_read_b128 v[178:181], v145 offset:53248
	ds_read_b128 v[182:185], v145 offset:54272
	ds_read_b128 v[186:189], v145 offset:55296
	ds_read_b128 v[190:193], v145 offset:56320
	global_load_lds_dwordx4 v[140:141], off
	v_lshl_add_u64 v[140:141], v[224:225], 0, s[10:11]
	s_mov_b32 m0, s58
	s_nop 0
	global_load_lds_dwordx4 v[140:141], off
	s_barrier
	s_waitcnt lgkmcnt(0)
	s_waitcnt lgkmcnt(0)
	v_mfma_f32_16x16x32_bf16 v[62:65], v[146:149], v[162:165], v[62:65]
	v_mfma_f32_16x16x32_bf16 v[54:57], v[154:157], v[162:165], v[54:57]
	v_mfma_f32_16x16x32_bf16 v[46:49], v[146:149], v[170:173], v[46:49]
	v_mfma_f32_16x16x32_bf16 v[38:41], v[154:157], v[170:173], v[38:41]
	v_mfma_f32_16x16x32_bf16 v[30:33], v[146:149], v[178:181], v[30:33]
	v_mfma_f32_16x16x32_bf16 v[22:25], v[154:157], v[178:181], v[22:25]
	v_mfma_f32_16x16x32_bf16 v[12:15], v[146:149], v[186:189], v[12:15]
	v_mfma_f32_16x16x32_bf16 v[4:7], v[154:157], v[186:189], v[4:7]
	v_mfma_f32_16x16x32_bf16 v[62:65], v[150:153], v[166:169], v[62:65]
	v_mfma_f32_16x16x32_bf16 v[54:57], v[158:161], v[166:169], v[54:57]
	v_mfma_f32_16x16x32_bf16 v[46:49], v[150:153], v[174:177], v[46:49]
	v_mfma_f32_16x16x32_bf16 v[38:41], v[158:161], v[174:177], v[38:41]
	v_mfma_f32_16x16x32_bf16 v[30:33], v[150:153], v[182:185], v[30:33]
	v_mfma_f32_16x16x32_bf16 v[22:25], v[158:161], v[182:185], v[22:25]
	v_mfma_f32_16x16x32_bf16 v[12:15], v[150:153], v[190:193], v[12:15]
	v_mfma_f32_16x16x32_bf16 v[4:7], v[158:161], v[190:193], v[4:7]
	s_barrier
	s_add_u32 s18, s18, 0x40080
	s_addc_u32 s19, s19, 0
	s_add_i32 s22, s22, s51
	v_lshl_add_u64 v[140:141], s[18:19], 0, v[16:17]
	s_mov_b32 m0, s22
	s_nop 0
	global_load_lds_dwordx4 v[140:141], off
	v_lshl_add_u64 v[140:141], s[18:19], 0, v[130:131]
	s_add_i32 m0, s22, 0x2000
	s_nop 0
	global_load_lds_dwordx4 v[140:141], off
	s_cmp_eq_u32 s82, 12
	s_cbranch_scc0 .Lvl_1
	s_waitcnt vmcnt(6)
.Lvl_1:
	s_waitcnt vmcnt(10)
	s_barrier
	v_mfma_f32_16x16x32_bf16 v[58:61], v[194:197], v[162:165], v[58:61]
	v_mfma_f32_16x16x32_bf16 v[50:53], v[212:215], v[162:165], v[50:53]
	v_mfma_f32_16x16x32_bf16 v[42:45], v[194:197], v[170:173], v[42:45]
	v_mfma_f32_16x16x32_bf16 v[34:37], v[212:215], v[170:173], v[34:37]
	v_mfma_f32_16x16x32_bf16 v[26:29], v[194:197], v[178:181], v[26:29]
	v_mfma_f32_16x16x32_bf16 v[18:21], v[212:215], v[178:181], v[18:21]
	v_mfma_f32_16x16x32_bf16 v[8:11], v[194:197], v[186:189], v[8:11]
	v_mfma_f32_16x16x32_bf16 v[0:3], v[212:215], v[186:189], v[0:3]
	v_mfma_f32_16x16x32_bf16 v[58:61], v[208:211], v[166:169], v[58:61]
	v_mfma_f32_16x16x32_bf16 v[50:53], v[216:219], v[166:169], v[50:53]
	v_mfma_f32_16x16x32_bf16 v[42:45], v[208:211], v[174:177], v[42:45]
	v_mfma_f32_16x16x32_bf16 v[34:37], v[216:219], v[174:177], v[34:37]
	v_mfma_f32_16x16x32_bf16 v[26:29], v[208:211], v[182:185], v[26:29]
	v_mfma_f32_16x16x32_bf16 v[18:21], v[216:219], v[182:185], v[18:21]
	v_mfma_f32_16x16x32_bf16 v[8:11], v[208:211], v[190:193], v[8:11]
	v_mfma_f32_16x16x32_bf16 v[0:3], v[216:219], v[190:193], v[0:3]
	s_add_i32 s82, s82, 2
	s_add_u32 s61, s61, 0x100
	s_addc_u32 s79, s79, 0
	s_add_u32 s16, s16, 0x100
	s_addc_u32 s17, s17, 0
	s_cmp_gt_u32 s82, 13
	s_barrier
	s_cbranch_scc0 .LBB0_147
	v_mul_f32_e32 v208, 0xbfb8aa3b, v126
	v_mul_f32_e32 v209, 0xbfb8aa3b, v127
	v_mul_f32_e32 v210, 0xbfb8aa3b, v128
	v_mul_f32_e32 v211, 0xbfb8aa3b, v129
	v_mul_f32_e32 v212, 0xbfb8aa3b, v118
	v_mul_f32_e32 v213, 0xbfb8aa3b, v119
	v_mul_f32_e32 v214, 0xbfb8aa3b, v120
	v_mul_f32_e32 v215, 0xbfb8aa3b, v121
	v_exp_f32_e32 v208, v208
	v_exp_f32_e32 v209, v209
	v_exp_f32_e32 v210, v210
	v_exp_f32_e32 v211, v211
	v_exp_f32_e32 v212, v212
	v_exp_f32_e32 v213, v213
	v_exp_f32_e32 v214, v214
	v_exp_f32_e32 v215, v215
	v_add_f32_e32 v208, 1.0, v208
	v_add_f32_e32 v209, 1.0, v209
	v_add_f32_e32 v210, 1.0, v210
	v_add_f32_e32 v211, 1.0, v211
	v_add_f32_e32 v212, 1.0, v212
	v_add_f32_e32 v213, 1.0, v213
	v_add_f32_e32 v214, 1.0, v214
	v_add_f32_e32 v215, 1.0, v215
	v_rcp_f32_e32 v208, v208
	v_rcp_f32_e32 v209, v209
	v_rcp_f32_e32 v210, v210
	v_rcp_f32_e32 v211, v211
	v_rcp_f32_e32 v212, v212
	v_rcp_f32_e32 v213, v213
	v_rcp_f32_e32 v214, v214
	v_rcp_f32_e32 v215, v215
	v_mul_f32_e32 v216, v126, v208
	v_mul_f32_e32 v217, v127, v209
	v_mul_f32_e32 v218, v128, v210
	v_mul_f32_e32 v219, v129, v211
	v_mul_f32_e32 v220, v118, v212
	v_mul_f32_e32 v221, v119, v213
	v_mul_f32_e32 v222, v120, v214
	v_mul_f32_e32 v223, v121, v215
	v_mul_f32_e32 v216, v216, v122
	v_mul_f32_e32 v217, v217, v123
	v_mul_f32_e32 v218, v218, v124
	v_mul_f32_e32 v219, v219, v125
	v_mul_f32_e32 v220, v220, v114
	v_mul_f32_e32 v221, v221, v115
	v_mul_f32_e32 v222, v222, v116
	v_mul_f32_e32 v223, v223, v117
	v_lshl_or_b32 v148, s2, 7, v144
	v_lshl_add_u32 v146, s14, 8, v142
	v_ashrrev_i32_e32 v149, 31, v148
	v_mov_b64_e32 v[140:141], s[94:95]
	v_mad_i64_i32 v[150:151], s[16:17], v146, s65, v[140:141]
	v_lshlrev_b64 v[114:115], 1, v[148:149]
	v_lshl_add_u64 v[120:121], v[150:151], 0, v[114:115]
	v_cvt_pk_bf16_f32 v116, v216, v217
	v_cvt_pk_bf16_f32 v117, v218, v219
	v_cvt_pk_bf16_f32 v118, v220, v221
	v_cvt_pk_bf16_f32 v119, v222, v223
	global_store_dwordx4 v[120:121], v[116:119], off
	v_mul_f32_e32 v208, 0xbfb8aa3b, v110
	v_mul_f32_e32 v209, 0xbfb8aa3b, v111
	v_mul_f32_e32 v210, 0xbfb8aa3b, v112
	v_mul_f32_e32 v211, 0xbfb8aa3b, v113
	v_mul_f32_e32 v212, 0xbfb8aa3b, v102
	v_mul_f32_e32 v213, 0xbfb8aa3b, v103
	v_mul_f32_e32 v214, 0xbfb8aa3b, v104
	v_mul_f32_e32 v215, 0xbfb8aa3b, v105
	v_exp_f32_e32 v208, v208
	v_exp_f32_e32 v209, v209
	v_exp_f32_e32 v210, v210
	v_exp_f32_e32 v211, v211
	v_exp_f32_e32 v212, v212
	v_exp_f32_e32 v213, v213
	v_exp_f32_e32 v214, v214
	v_exp_f32_e32 v215, v215
	v_add_f32_e32 v208, 1.0, v208
	v_add_f32_e32 v209, 1.0, v209
	v_add_f32_e32 v210, 1.0, v210
	v_add_f32_e32 v211, 1.0, v211
	v_add_f32_e32 v212, 1.0, v212
	v_add_f32_e32 v213, 1.0, v213
	v_add_f32_e32 v214, 1.0, v214
	v_add_f32_e32 v215, 1.0, v215
	v_rcp_f32_e32 v208, v208
	v_rcp_f32_e32 v209, v209
	v_rcp_f32_e32 v210, v210
	v_rcp_f32_e32 v211, v211
	v_rcp_f32_e32 v212, v212
	v_rcp_f32_e32 v213, v213
	v_rcp_f32_e32 v214, v214
	v_rcp_f32_e32 v215, v215
	v_mul_f32_e32 v216, v110, v208
	v_mul_f32_e32 v217, v111, v209
	v_mul_f32_e32 v218, v112, v210
	v_mul_f32_e32 v219, v113, v211
	v_mul_f32_e32 v220, v102, v212
	v_mul_f32_e32 v221, v103, v213
	v_mul_f32_e32 v222, v104, v214
	v_mul_f32_e32 v223, v105, v215
	v_mul_f32_e32 v216, v216, v106
	v_mul_f32_e32 v217, v217, v107
	v_mul_f32_e32 v218, v218, v108
	v_mul_f32_e32 v219, v219, v109
	v_mul_f32_e32 v220, v220, v98
	v_mul_f32_e32 v221, v221, v99
	v_mul_f32_e32 v222, v222, v100
	v_mul_f32_e32 v223, v223, v101
	v_or_b32_e32 v116, 16, v146
	v_mad_i64_i32 v[116:117], s[16:17], v116, s65, v[140:141]
	v_lshl_add_u64 v[102:103], v[116:117], 0, v[114:115]
	v_cvt_pk_bf16_f32 v98, v216, v217
	v_cvt_pk_bf16_f32 v99, v218, v219
	v_cvt_pk_bf16_f32 v100, v220, v221
	v_cvt_pk_bf16_f32 v101, v222, v223
	global_store_dwordx4 v[102:103], v[98:101], off
	v_mul_f32_e32 v208, 0xbfb8aa3b, v94
	v_mul_f32_e32 v209, 0xbfb8aa3b, v95
	v_mul_f32_e32 v210, 0xbfb8aa3b, v96
	v_mul_f32_e32 v211, 0xbfb8aa3b, v97
	v_mul_f32_e32 v212, 0xbfb8aa3b, v86
	v_mul_f32_e32 v213, 0xbfb8aa3b, v87
	v_mul_f32_e32 v214, 0xbfb8aa3b, v88
	v_mul_f32_e32 v215, 0xbfb8aa3b, v89
	v_exp_f32_e32 v208, v208
	v_exp_f32_e32 v209, v209
	v_exp_f32_e32 v210, v210
	v_exp_f32_e32 v211, v211
	v_exp_f32_e32 v212, v212
	v_exp_f32_e32 v213, v213
	v_exp_f32_e32 v214, v214
	v_exp_f32_e32 v215, v215
	v_add_f32_e32 v208, 1.0, v208
	v_add_f32_e32 v209, 1.0, v209
	v_add_f32_e32 v210, 1.0, v210
	v_add_f32_e32 v211, 1.0, v211
	v_add_f32_e32 v212, 1.0, v212
	v_add_f32_e32 v213, 1.0, v213
	v_add_f32_e32 v214, 1.0, v214
	v_add_f32_e32 v215, 1.0, v215
	v_rcp_f32_e32 v208, v208
	v_rcp_f32_e32 v209, v209
	v_rcp_f32_e32 v210, v210
	v_rcp_f32_e32 v211, v211
	v_rcp_f32_e32 v212, v212
	v_rcp_f32_e32 v213, v213
	v_rcp_f32_e32 v214, v214
	v_rcp_f32_e32 v215, v215
	v_mul_f32_e32 v216, v94, v208
	v_mul_f32_e32 v217, v95, v209
	v_mul_f32_e32 v218, v96, v210
	v_mul_f32_e32 v219, v97, v211
	v_mul_f32_e32 v220, v86, v212
	v_mul_f32_e32 v221, v87, v213
	v_mul_f32_e32 v222, v88, v214
	v_mul_f32_e32 v223, v89, v215
	v_mul_f32_e32 v216, v216, v90
	v_mul_f32_e32 v217, v217, v91
	v_mul_f32_e32 v218, v218, v92
	v_mul_f32_e32 v219, v219, v93
	v_mul_f32_e32 v220, v220, v82
	v_mul_f32_e32 v221, v221, v83
	v_mul_f32_e32 v222, v222, v84
	v_mul_f32_e32 v223, v223, v85
	v_or_b32_e32 v98, 32, v146
	v_mad_i64_i32 v[98:99], s[16:17], v98, s65, v[140:141]
	v_lshl_add_u64 v[86:87], v[98:99], 0, v[114:115]
	v_cvt_pk_bf16_f32 v82, v216, v217
	v_cvt_pk_bf16_f32 v83, v218, v219
	v_cvt_pk_bf16_f32 v84, v220, v221
	v_cvt_pk_bf16_f32 v85, v222, v223
	global_store_dwordx4 v[86:87], v[82:85], off
	v_mul_f32_e32 v208, 0xbfb8aa3b, v78
	v_mul_f32_e32 v209, 0xbfb8aa3b, v79
	v_mul_f32_e32 v210, 0xbfb8aa3b, v80
	v_mul_f32_e32 v211, 0xbfb8aa3b, v81
	v_mul_f32_e32 v212, 0xbfb8aa3b, v70
	v_mul_f32_e32 v213, 0xbfb8aa3b, v71
	v_mul_f32_e32 v214, 0xbfb8aa3b, v72
	v_mul_f32_e32 v215, 0xbfb8aa3b, v73
	v_exp_f32_e32 v208, v208
	v_exp_f32_e32 v209, v209
	v_exp_f32_e32 v210, v210
	v_exp_f32_e32 v211, v211
	v_exp_f32_e32 v212, v212
	v_exp_f32_e32 v213, v213
	v_exp_f32_e32 v214, v214
	v_exp_f32_e32 v215, v215
	v_add_f32_e32 v208, 1.0, v208
	v_add_f32_e32 v209, 1.0, v209
	v_add_f32_e32 v210, 1.0, v210
	v_add_f32_e32 v211, 1.0, v211
	v_add_f32_e32 v212, 1.0, v212
	v_add_f32_e32 v213, 1.0, v213
	v_add_f32_e32 v214, 1.0, v214
	v_add_f32_e32 v215, 1.0, v215
	v_rcp_f32_e32 v208, v208
	v_rcp_f32_e32 v209, v209
	v_rcp_f32_e32 v210, v210
	v_rcp_f32_e32 v211, v211
	v_rcp_f32_e32 v212, v212
	v_rcp_f32_e32 v213, v213
	v_rcp_f32_e32 v214, v214
	v_rcp_f32_e32 v215, v215
	v_mul_f32_e32 v216, v78, v208
	v_mul_f32_e32 v217, v79, v209
	v_mul_f32_e32 v218, v80, v210
	v_mul_f32_e32 v219, v81, v211
	v_mul_f32_e32 v220, v70, v212
	v_mul_f32_e32 v221, v71, v213
	v_mul_f32_e32 v222, v72, v214
	v_mul_f32_e32 v223, v73, v215
	v_mul_f32_e32 v216, v216, v74
	v_mul_f32_e32 v217, v217, v75
	v_mul_f32_e32 v218, v218, v76
	v_mul_f32_e32 v219, v219, v77
	v_mul_f32_e32 v220, v220, v66
	v_mul_f32_e32 v221, v221, v67
	v_mul_f32_e32 v222, v222, v68
	v_mul_f32_e32 v223, v223, v69
	v_or_b32_e32 v82, 48, v146
	v_mad_i64_i32 v[82:83], s[16:17], v82, s65, v[140:141]
	v_lshl_add_u64 v[70:71], v[82:83], 0, v[114:115]
	v_cvt_pk_bf16_f32 v66, v216, v217
	v_cvt_pk_bf16_f32 v67, v218, v219
	v_cvt_pk_bf16_f32 v68, v220, v221
	v_cvt_pk_bf16_f32 v69, v222, v223
	global_store_dwordx4 v[70:71], v[66:69], off
	v_mul_f32_e32 v208, 0xbfb8aa3b, v62
	v_mul_f32_e32 v209, 0xbfb8aa3b, v63
	v_mul_f32_e32 v210, 0xbfb8aa3b, v64
	v_mul_f32_e32 v211, 0xbfb8aa3b, v65
	v_mul_f32_e32 v212, 0xbfb8aa3b, v54
	v_mul_f32_e32 v213, 0xbfb8aa3b, v55
	v_mul_f32_e32 v214, 0xbfb8aa3b, v56
	v_mul_f32_e32 v215, 0xbfb8aa3b, v57
	v_exp_f32_e32 v208, v208
	v_exp_f32_e32 v209, v209
	v_exp_f32_e32 v210, v210
	v_exp_f32_e32 v211, v211
	v_exp_f32_e32 v212, v212
	v_exp_f32_e32 v213, v213
	v_exp_f32_e32 v214, v214
	v_exp_f32_e32 v215, v215
	v_add_f32_e32 v208, 1.0, v208
	v_add_f32_e32 v209, 1.0, v209
	v_add_f32_e32 v210, 1.0, v210
	v_add_f32_e32 v211, 1.0, v211
	v_add_f32_e32 v212, 1.0, v212
	v_add_f32_e32 v213, 1.0, v213
	v_add_f32_e32 v214, 1.0, v214
	v_add_f32_e32 v215, 1.0, v215
	v_rcp_f32_e32 v208, v208
	v_rcp_f32_e32 v209, v209
	v_rcp_f32_e32 v210, v210
	v_rcp_f32_e32 v211, v211
	v_rcp_f32_e32 v212, v212
	v_rcp_f32_e32 v213, v213
	v_rcp_f32_e32 v214, v214
	v_rcp_f32_e32 v215, v215
	v_mul_f32_e32 v216, v62, v208
	v_mul_f32_e32 v217, v63, v209
	v_mul_f32_e32 v218, v64, v210
	v_mul_f32_e32 v219, v65, v211
	v_mul_f32_e32 v220, v54, v212
	v_mul_f32_e32 v221, v55, v213
	v_mul_f32_e32 v222, v56, v214
	v_mul_f32_e32 v223, v57, v215
	v_mul_f32_e32 v216, v216, v58
	v_mul_f32_e32 v217, v217, v59
	v_mul_f32_e32 v218, v218, v60
	v_mul_f32_e32 v219, v219, v61
	v_mul_f32_e32 v220, v220, v50
	v_mul_f32_e32 v221, v221, v51
	v_mul_f32_e32 v222, v222, v52
	v_mul_f32_e32 v223, v223, v53
	v_add_u32_e32 v66, 0x80, v146
	v_mad_i64_i32 v[66:67], s[16:17], v66, s65, v[140:141]
	v_lshl_add_u64 v[54:55], v[66:67], 0, v[114:115]
	v_cvt_pk_bf16_f32 v50, v216, v217
	v_cvt_pk_bf16_f32 v51, v218, v219
	v_cvt_pk_bf16_f32 v52, v220, v221
	v_cvt_pk_bf16_f32 v53, v222, v223
	global_store_dwordx4 v[54:55], v[50:53], off
	v_mul_f32_e32 v208, 0xbfb8aa3b, v46
	v_mul_f32_e32 v209, 0xbfb8aa3b, v47
	v_mul_f32_e32 v210, 0xbfb8aa3b, v48
	v_mul_f32_e32 v211, 0xbfb8aa3b, v49
	v_mul_f32_e32 v212, 0xbfb8aa3b, v38
	v_mul_f32_e32 v213, 0xbfb8aa3b, v39
	v_mul_f32_e32 v214, 0xbfb8aa3b, v40
	v_mul_f32_e32 v215, 0xbfb8aa3b, v41
	v_exp_f32_e32 v208, v208
	v_exp_f32_e32 v209, v209
	v_exp_f32_e32 v210, v210
	v_exp_f32_e32 v211, v211
	v_exp_f32_e32 v212, v212
	v_exp_f32_e32 v213, v213
	v_exp_f32_e32 v214, v214
	v_exp_f32_e32 v215, v215
	v_add_f32_e32 v208, 1.0, v208
	v_add_f32_e32 v209, 1.0, v209
	v_add_f32_e32 v210, 1.0, v210
	v_add_f32_e32 v211, 1.0, v211
	v_add_f32_e32 v212, 1.0, v212
	v_add_f32_e32 v213, 1.0, v213
	v_add_f32_e32 v214, 1.0, v214
	v_add_f32_e32 v215, 1.0, v215
	v_rcp_f32_e32 v208, v208
	v_rcp_f32_e32 v209, v209
	v_rcp_f32_e32 v210, v210
	v_rcp_f32_e32 v211, v211
	v_rcp_f32_e32 v212, v212
	v_rcp_f32_e32 v213, v213
	v_rcp_f32_e32 v214, v214
	v_rcp_f32_e32 v215, v215
	v_mul_f32_e32 v216, v46, v208
	v_mul_f32_e32 v217, v47, v209
	v_mul_f32_e32 v218, v48, v210
	v_mul_f32_e32 v219, v49, v211
	v_mul_f32_e32 v220, v38, v212
	v_mul_f32_e32 v221, v39, v213
	v_mul_f32_e32 v222, v40, v214
	v_mul_f32_e32 v223, v41, v215
	v_mul_f32_e32 v216, v216, v42
	v_mul_f32_e32 v217, v217, v43
	v_mul_f32_e32 v218, v218, v44
	v_mul_f32_e32 v219, v219, v45
	v_mul_f32_e32 v220, v220, v34
	v_mul_f32_e32 v221, v221, v35
	v_mul_f32_e32 v222, v222, v36
	v_mul_f32_e32 v223, v223, v37
	v_add_u32_e32 v50, 0x90, v146
	v_mad_i64_i32 v[50:51], s[16:17], v50, s65, v[140:141]
	v_lshl_add_u64 v[38:39], v[50:51], 0, v[114:115]
	v_cvt_pk_bf16_f32 v34, v216, v217
	v_cvt_pk_bf16_f32 v35, v218, v219
	v_cvt_pk_bf16_f32 v36, v220, v221
	v_cvt_pk_bf16_f32 v37, v222, v223
	global_store_dwordx4 v[38:39], v[34:37], off
	v_mul_f32_e32 v208, 0xbfb8aa3b, v30
	v_mul_f32_e32 v209, 0xbfb8aa3b, v31
	v_mul_f32_e32 v210, 0xbfb8aa3b, v32
	v_mul_f32_e32 v211, 0xbfb8aa3b, v33
	v_mul_f32_e32 v212, 0xbfb8aa3b, v22
	v_mul_f32_e32 v213, 0xbfb8aa3b, v23
	v_mul_f32_e32 v214, 0xbfb8aa3b, v24
	v_mul_f32_e32 v215, 0xbfb8aa3b, v25
	v_exp_f32_e32 v208, v208
	v_exp_f32_e32 v209, v209
	v_exp_f32_e32 v210, v210
	v_exp_f32_e32 v211, v211
	v_exp_f32_e32 v212, v212
	v_exp_f32_e32 v213, v213
	v_exp_f32_e32 v214, v214
	v_exp_f32_e32 v215, v215
	v_add_f32_e32 v208, 1.0, v208
	v_add_f32_e32 v209, 1.0, v209
	v_add_f32_e32 v210, 1.0, v210
	v_add_f32_e32 v211, 1.0, v211
	v_add_f32_e32 v212, 1.0, v212
	v_add_f32_e32 v213, 1.0, v213
	v_add_f32_e32 v214, 1.0, v214
	v_add_f32_e32 v215, 1.0, v215
	v_rcp_f32_e32 v208, v208
	v_rcp_f32_e32 v209, v209
	v_rcp_f32_e32 v210, v210
	v_rcp_f32_e32 v211, v211
	v_rcp_f32_e32 v212, v212
	v_rcp_f32_e32 v213, v213
	v_rcp_f32_e32 v214, v214
	v_rcp_f32_e32 v215, v215
	v_mul_f32_e32 v216, v30, v208
	v_mul_f32_e32 v217, v31, v209
	v_mul_f32_e32 v218, v32, v210
	v_mul_f32_e32 v219, v33, v211
	v_mul_f32_e32 v220, v22, v212
	v_mul_f32_e32 v221, v23, v213
	v_mul_f32_e32 v222, v24, v214
	v_mul_f32_e32 v223, v25, v215
	v_mul_f32_e32 v216, v216, v26
	v_mul_f32_e32 v217, v217, v27
	v_mul_f32_e32 v218, v218, v28
	v_mul_f32_e32 v219, v219, v29
	v_mul_f32_e32 v220, v220, v18
	v_mul_f32_e32 v221, v221, v19
	v_mul_f32_e32 v222, v222, v20
	v_mul_f32_e32 v223, v223, v21
	v_add_u32_e32 v34, 0xa0, v146
	v_mad_i64_i32 v[34:35], s[16:17], v34, s65, v[140:141]
	v_lshl_add_u64 v[22:23], v[34:35], 0, v[114:115]
	v_cvt_pk_bf16_f32 v18, v216, v217
	v_cvt_pk_bf16_f32 v19, v218, v219
	v_cvt_pk_bf16_f32 v20, v220, v221
	v_cvt_pk_bf16_f32 v21, v222, v223
	global_store_dwordx4 v[22:23], v[18:21], off
	v_mul_f32_e32 v208, 0xbfb8aa3b, v12
	v_mul_f32_e32 v209, 0xbfb8aa3b, v13
	v_mul_f32_e32 v210, 0xbfb8aa3b, v14
	v_mul_f32_e32 v211, 0xbfb8aa3b, v15
	v_mul_f32_e32 v212, 0xbfb8aa3b, v4
	v_mul_f32_e32 v213, 0xbfb8aa3b, v5
	v_mul_f32_e32 v214, 0xbfb8aa3b, v6
	v_mul_f32_e32 v215, 0xbfb8aa3b, v7
	v_exp_f32_e32 v208, v208
	v_exp_f32_e32 v209, v209
	v_exp_f32_e32 v210, v210
	v_exp_f32_e32 v211, v211
	v_exp_f32_e32 v212, v212
	v_exp_f32_e32 v213, v213
	v_exp_f32_e32 v214, v214
	v_exp_f32_e32 v215, v215
	v_add_f32_e32 v208, 1.0, v208
	v_add_f32_e32 v209, 1.0, v209
	v_add_f32_e32 v210, 1.0, v210
	v_add_f32_e32 v211, 1.0, v211
	v_add_f32_e32 v212, 1.0, v212
	v_add_f32_e32 v213, 1.0, v213
	v_add_f32_e32 v214, 1.0, v214
	v_add_f32_e32 v215, 1.0, v215
	v_rcp_f32_e32 v208, v208
	v_rcp_f32_e32 v209, v209
	v_rcp_f32_e32 v210, v210
	v_rcp_f32_e32 v211, v211
	v_rcp_f32_e32 v212, v212
	v_rcp_f32_e32 v213, v213
	v_rcp_f32_e32 v214, v214
	v_rcp_f32_e32 v215, v215
	v_mul_f32_e32 v216, v12, v208
	v_mul_f32_e32 v217, v13, v209
	v_mul_f32_e32 v218, v14, v210
	v_mul_f32_e32 v219, v15, v211
	v_mul_f32_e32 v220, v4, v212
	v_mul_f32_e32 v221, v5, v213
	v_mul_f32_e32 v222, v6, v214
	v_mul_f32_e32 v223, v7, v215
	v_mul_f32_e32 v216, v216, v8
	v_mul_f32_e32 v217, v217, v9
	v_mul_f32_e32 v218, v218, v10
	v_mul_f32_e32 v219, v219, v11
	v_mul_f32_e32 v220, v220, v0
	v_mul_f32_e32 v221, v221, v1
	v_mul_f32_e32 v222, v222, v2
	v_mul_f32_e32 v223, v223, v3
	v_add_u32_e32 v18, 0xb0, v146
	v_mad_i64_i32 v[18:19], s[16:17], v18, s65, v[140:141]
	v_lshl_add_u64 v[4:5], v[18:19], 0, v[114:115]
	v_cvt_pk_bf16_f32 v0, v216, v217
	v_cvt_pk_bf16_f32 v1, v218, v219
	v_cvt_pk_bf16_f32 v2, v220, v221
	v_cvt_pk_bf16_f32 v3, v222, v223
	global_store_dwordx4 v[4:5], v[0:3], off
	s_and_b64 vcc, exec, s[38:39]
	s_mov_b32 s2, s8
	s_mov_b32 s14, s28
	s_mov_b64 s[16:17], s[42:43]
	s_mov_b64 s[18:19], s[40:41]
	s_cbranch_vccz .LBB0_144
	s_waitcnt vmcnt(0)
	s_cmpk_gt_u32 s48, 0xff
	s_cbranch_scc1 .LBB0_151
	s_barrier

.LBB0_174:
	s_add_u32 s40, s22, 0x100
	s_addc_u32 s41, s23, 0
	s_add_i32 s83, 0, 0x10000
	v_add_u32_e32 v148, s83, v157
	ds_read_b128 v[130:133], v148
	ds_read_b128 v[134:137], v148 offset:1024
	ds_read_b128 v[138:141], v148 offset:2048
	ds_read_b128 v[148:151], v148 offset:3072
	s_cmp_eq_u32 s82, 12
	s_cselect_b32 s49, s9, s41
	s_cselect_b32 s48, s12, s40
	s_cselect_b32 s43, s5, s79
	s_cselect_b32 s42, s34, s61
	v_lshl_add_u64 v[188:189], s[22:23], 0, v[146:147]
	s_add_i32 m0, s19, 0xc000
	ds_read_b128 v[152:155], v159
	ds_read_b128 v[160:163], v159 offset:1024
	ds_read_b128 v[164:167], v159 offset:2048
	ds_read_b128 v[168:171], v159 offset:3072
	ds_read_b128 v[172:175], v159 offset:4096
	ds_read_b128 v[176:179], v159 offset:5120
	ds_read_b128 v[180:183], v159 offset:6144
	ds_read_b128 v[184:187], v159 offset:7168
	global_load_lds_dwordx4 v[188:189], off
	v_lshl_add_u64 v[188:189], s[22:23], 0, v[144:145]
	s_add_i32 m0, s19, 0xe000
	s_nop 0
	global_load_lds_dwordx4 v[188:189], off
	s_waitcnt lgkmcnt(8)
	s_cmp_eq_u32 s82, -2
	s_cbranch_scc1 .Lvw_2_1
	s_waitcnt vmcnt(10)
.Lvw_2_1:
	s_barrier
	s_waitcnt lgkmcnt(0)
	s_waitcnt lgkmcnt(0)
	v_mfma_f32_16x16x32_bf16 v[126:129], v[130:133], v[152:155], v[126:129]
	v_mfma_f32_16x16x32_bf16 v[122:125], v[138:141], v[152:155], v[122:125]
	v_mfma_f32_16x16x32_bf16 v[118:121], v[130:133], v[164:167], v[118:121]
	v_mfma_f32_16x16x32_bf16 v[106:109], v[138:141], v[164:167], v[106:109]
	v_mfma_f32_16x16x32_bf16 v[102:105], v[130:133], v[172:175], v[102:105]
	v_mfma_f32_16x16x32_bf16 v[90:93], v[138:141], v[172:175], v[90:93]
	v_mfma_f32_16x16x32_bf16 v[86:89], v[130:133], v[180:183], v[86:89]
	v_mfma_f32_16x16x32_bf16 v[74:77], v[138:141], v[180:183], v[74:77]
	v_mfma_f32_16x16x32_bf16 v[126:129], v[134:137], v[160:163], v[126:129]
	v_mfma_f32_16x16x32_bf16 v[122:125], v[148:151], v[160:163], v[122:125]
	v_mfma_f32_16x16x32_bf16 v[118:121], v[134:137], v[168:171], v[118:121]
	v_mfma_f32_16x16x32_bf16 v[106:109], v[148:151], v[168:171], v[106:109]
	v_mfma_f32_16x16x32_bf16 v[102:105], v[134:137], v[176:179], v[102:105]
	v_mfma_f32_16x16x32_bf16 v[90:93], v[148:151], v[176:179], v[90:93]
	v_mfma_f32_16x16x32_bf16 v[86:89], v[134:137], v[184:187], v[86:89]
	v_mfma_f32_16x16x32_bf16 v[74:77], v[148:151], v[184:187], v[74:77]
	s_barrier
	s_add_i32 s84, 0, 0x14000
	v_add_u32_e32 v196, s84, v157
	s_add_i32 s22, s83, s52
	ds_read_b128 v[188:191], v196
	ds_read_b128 v[192:195], v196 offset:1024
	ds_read_b128 v[208:211], v196 offset:2048
	ds_read_b128 v[212:215], v196 offset:3072
	v_lshl_add_u64 v[196:197], s[42:43], 0, v[16:17]
	s_mov_b32 m0, s22
	v_lshl_add_u64 v[216:217], s[42:43], 0, v[142:143]
	global_load_lds_dwordx4 v[196:197], off
	s_add_i32 m0, s22, 0x2000
	s_nop 0
	global_load_lds_dwordx4 v[216:217], off
	s_cmp_eq_u32 s82, -2
	s_cbranch_scc1 .Lvw_2_2
	s_waitcnt vmcnt(10)
.Lvw_2_2:
	s_barrier
	s_waitcnt lgkmcnt(0)
	s_waitcnt lgkmcnt(0)
	v_mfma_f32_16x16x32_bf16 v[114:117], v[188:191], v[152:155], v[114:117]
	v_mfma_f32_16x16x32_bf16 v[110:113], v[208:211], v[152:155], v[110:113]
	v_mfma_f32_16x16x32_bf16 v[98:101], v[188:191], v[164:167], v[98:101]
	v_mfma_f32_16x16x32_bf16 v[94:97], v[208:211], v[164:167], v[94:97]
	v_mfma_f32_16x16x32_bf16 v[82:85], v[188:191], v[172:175], v[82:85]
	v_mfma_f32_16x16x32_bf16 v[78:81], v[208:211], v[172:175], v[78:81]
	v_mfma_f32_16x16x32_bf16 v[70:73], v[188:191], v[180:183], v[70:73]
	v_mfma_f32_16x16x32_bf16 v[66:69], v[208:211], v[180:183], v[66:69]
	v_mfma_f32_16x16x32_bf16 v[114:117], v[192:195], v[160:163], v[114:117]
	v_mfma_f32_16x16x32_bf16 v[110:113], v[212:215], v[160:163], v[110:113]
	v_mfma_f32_16x16x32_bf16 v[98:101], v[192:195], v[168:171], v[98:101]
	v_mfma_f32_16x16x32_bf16 v[94:97], v[212:215], v[168:171], v[94:97]
	v_mfma_f32_16x16x32_bf16 v[82:85], v[192:195], v[176:179], v[82:85]
	v_mfma_f32_16x16x32_bf16 v[78:81], v[212:215], v[176:179], v[78:81]
	v_mfma_f32_16x16x32_bf16 v[70:73], v[192:195], v[184:187], v[70:73]
	v_mfma_f32_16x16x32_bf16 v[66:69], v[212:215], v[184:187], v[66:69]
	s_mov_b32 m0, s19
	v_lshl_add_u64 v[218:219], s[48:49], 0, v[16:17]
	s_barrier
	ds_read_b128 v[152:155], v159 offset:16384
	ds_read_b128 v[160:163], v159 offset:17408
	ds_read_b128 v[164:167], v159 offset:18432
	ds_read_b128 v[168:171], v159 offset:19456
	ds_read_b128 v[172:175], v159 offset:20480
	ds_read_b128 v[176:179], v159 offset:21504
	ds_read_b128 v[180:183], v159 offset:22528
	ds_read_b128 v[184:187], v159 offset:23552
	global_load_lds_dwordx4 v[218:219], off
	v_lshl_add_u64 v[220:221], s[48:49], 0, v[142:143]
	s_mov_b32 m0, s54
	s_nop 0
	global_load_lds_dwordx4 v[220:221], off
	s_barrier
	s_waitcnt lgkmcnt(0)
	s_waitcnt lgkmcnt(0)
	v_mfma_f32_16x16x32_bf16 v[62:65], v[130:133], v[152:155], v[62:65]
	v_mfma_f32_16x16x32_bf16 v[58:61], v[138:141], v[152:155], v[58:61]
	v_mfma_f32_16x16x32_bf16 v[54:57], v[130:133], v[164:167], v[54:57]
	v_mfma_f32_16x16x32_bf16 v[50:53], v[138:141], v[164:167], v[50:53]
	v_mfma_f32_16x16x32_bf16 v[46:49], v[130:133], v[172:175], v[46:49]
	v_mfma_f32_16x16x32_bf16 v[38:41], v[138:141], v[172:175], v[38:41]
	v_mfma_f32_16x16x32_bf16 v[30:33], v[130:133], v[180:183], v[30:33]
	v_mfma_f32_16x16x32_bf16 v[18:21], v[138:141], v[180:183], v[18:21]
	v_mfma_f32_16x16x32_bf16 v[62:65], v[134:137], v[160:163], v[62:65]
	v_mfma_f32_16x16x32_bf16 v[58:61], v[148:151], v[160:163], v[58:61]
	v_mfma_f32_16x16x32_bf16 v[54:57], v[134:137], v[168:171], v[54:57]
	v_mfma_f32_16x16x32_bf16 v[50:53], v[148:151], v[168:171], v[50:53]
	v_mfma_f32_16x16x32_bf16 v[46:49], v[134:137], v[176:179], v[46:49]
	v_mfma_f32_16x16x32_bf16 v[38:41], v[148:151], v[176:179], v[38:41]
	v_mfma_f32_16x16x32_bf16 v[30:33], v[134:137], v[184:187], v[30:33]
	v_mfma_f32_16x16x32_bf16 v[18:21], v[148:151], v[184:187], v[18:21]
	s_barrier
	s_add_u32 s22, s42, 0x40000
	s_addc_u32 s23, s43, 0
	s_add_i32 s83, s84, s52
	v_lshl_add_u64 v[130:131], s[22:23], 0, v[16:17]
	s_mov_b32 m0, s83
	s_nop 0
	global_load_lds_dwordx4 v[130:131], off
	v_lshl_add_u64 v[130:131], s[22:23], 0, v[142:143]
	s_add_i32 m0, s83, 0x2000
	s_nop 0
	global_load_lds_dwordx4 v[130:131], off
	s_waitcnt vmcnt(10)
	s_barrier
	v_mfma_f32_16x16x32_bf16 v[42:45], v[188:191], v[152:155], v[42:45]
	v_mfma_f32_16x16x32_bf16 v[34:37], v[208:211], v[152:155], v[34:37]
	v_mfma_f32_16x16x32_bf16 v[26:29], v[188:191], v[164:167], v[26:29]
	v_mfma_f32_16x16x32_bf16 v[22:25], v[208:211], v[164:167], v[22:25]
	v_mfma_f32_16x16x32_bf16 v[12:15], v[188:191], v[172:175], v[12:15]
	v_mfma_f32_16x16x32_bf16 v[8:11], v[208:211], v[172:175], v[8:11]
	v_mfma_f32_16x16x32_bf16 v[4:7], v[188:191], v[180:183], v[4:7]
	v_mfma_f32_16x16x32_bf16 v[0:3], v[208:211], v[180:183], v[0:3]
	v_mfma_f32_16x16x32_bf16 v[42:45], v[192:195], v[160:163], v[42:45]
	v_mfma_f32_16x16x32_bf16 v[34:37], v[212:215], v[160:163], v[34:37]
	v_mfma_f32_16x16x32_bf16 v[26:29], v[192:195], v[168:171], v[26:29]
	v_mfma_f32_16x16x32_bf16 v[22:25], v[212:215], v[168:171], v[22:25]
	v_mfma_f32_16x16x32_bf16 v[12:15], v[192:195], v[176:179], v[12:15]
	v_mfma_f32_16x16x32_bf16 v[8:11], v[212:215], v[176:179], v[8:11]
	v_mfma_f32_16x16x32_bf16 v[4:7], v[192:195], v[184:187], v[4:7]
	v_mfma_f32_16x16x32_bf16 v[0:3], v[212:215], v[184:187], v[0:3]
	s_add_i32 s83, 0, 0x18000
	v_add_u32_e32 v148, s83, v157
	s_barrier
	ds_read_b128 v[130:133], v148
	ds_read_b128 v[134:137], v148 offset:1024
	ds_read_b128 v[138:141], v148 offset:2048
	ds_read_b128 v[148:151], v148 offset:3072
	s_add_u32 s22, s48, 0x40000
	s_addc_u32 s23, s49, 0
	s_mov_b32 m0, s55
	v_lshl_add_u64 v[188:189], s[22:23], 0, v[16:17]
	ds_read_b128 v[152:155], v159 offset:32768
	ds_read_b128 v[160:163], v159 offset:33792
	ds_read_b128 v[164:167], v159 offset:34816
	ds_read_b128 v[168:171], v159 offset:35840
	ds_read_b128 v[172:175], v159 offset:36864
	ds_read_b128 v[176:179], v159 offset:37888
	ds_read_b128 v[180:183], v159 offset:38912
	ds_read_b128 v[184:187], v159 offset:39936
	global_load_lds_dwordx4 v[188:189], off
	v_lshl_add_u64 v[188:189], s[22:23], 0, v[142:143]
	s_mov_b32 m0, s56
	s_nop 0
	global_load_lds_dwordx4 v[188:189], off
	s_waitcnt lgkmcnt(8)
	s_waitcnt vmcnt(10)
	s_barrier
	s_waitcnt lgkmcnt(0)
	s_waitcnt lgkmcnt(0)
	v_mfma_f32_16x16x32_bf16 v[126:129], v[130:133], v[152:155], v[126:129]
	v_mfma_f32_16x16x32_bf16 v[122:125], v[138:141], v[152:155], v[122:125]
	v_mfma_f32_16x16x32_bf16 v[118:121], v[130:133], v[164:167], v[118:121]
	v_mfma_f32_16x16x32_bf16 v[106:109], v[138:141], v[164:167], v[106:109]
	v_mfma_f32_16x16x32_bf16 v[102:105], v[130:133], v[172:175], v[102:105]
	v_mfma_f32_16x16x32_bf16 v[90:93], v[138:141], v[172:175], v[90:93]
	v_mfma_f32_16x16x32_bf16 v[86:89], v[130:133], v[180:183], v[86:89]
	v_mfma_f32_16x16x32_bf16 v[74:77], v[138:141], v[180:183], v[74:77]
	v_mfma_f32_16x16x32_bf16 v[126:129], v[134:137], v[160:163], v[126:129]
	v_mfma_f32_16x16x32_bf16 v[122:125], v[148:151], v[160:163], v[122:125]
	v_mfma_f32_16x16x32_bf16 v[118:121], v[134:137], v[168:171], v[118:121]
	v_mfma_f32_16x16x32_bf16 v[106:109], v[148:151], v[168:171], v[106:109]
	v_mfma_f32_16x16x32_bf16 v[102:105], v[134:137], v[176:179], v[102:105]
	v_mfma_f32_16x16x32_bf16 v[90:93], v[148:151], v[176:179], v[90:93]
	v_mfma_f32_16x16x32_bf16 v[86:89], v[134:137], v[184:187], v[86:89]
	v_mfma_f32_16x16x32_bf16 v[74:77], v[148:151], v[184:187], v[74:77]
	s_barrier
	s_add_i32 s48, 0, 0x1c000
	s_add_i32 s22, s83, s52
	v_add_u32_e32 v212, s48, v157
	v_lshl_add_u64 v[196:197], v[196:197], 0, s[10:11]
	s_mov_b32 m0, s22
	ds_read_b128 v[188:191], v212
	ds_read_b128 v[192:195], v212 offset:1024
	ds_read_b128 v[208:211], v212 offset:2048
	ds_read_b128 v[212:215], v212 offset:3072
	global_load_lds_dwordx4 v[196:197], off
	v_lshl_add_u64 v[196:197], v[216:217], 0, s[10:11]
	s_add_i32 m0, s22, 0x2000
	s_nop 0
	global_load_lds_dwordx4 v[196:197], off
	s_waitcnt vmcnt(10)
	s_barrier
	s_waitcnt lgkmcnt(0)
	s_waitcnt lgkmcnt(0)
	v_mfma_f32_16x16x32_bf16 v[114:117], v[188:191], v[152:155], v[114:117]
	v_mfma_f32_16x16x32_bf16 v[110:113], v[208:211], v[152:155], v[110:113]
	v_mfma_f32_16x16x32_bf16 v[98:101], v[188:191], v[164:167], v[98:101]
	v_mfma_f32_16x16x32_bf16 v[94:97], v[208:211], v[164:167], v[94:97]
	v_mfma_f32_16x16x32_bf16 v[82:85], v[188:191], v[172:175], v[82:85]
	v_mfma_f32_16x16x32_bf16 v[78:81], v[208:211], v[172:175], v[78:81]
	v_mfma_f32_16x16x32_bf16 v[70:73], v[188:191], v[180:183], v[70:73]
	v_mfma_f32_16x16x32_bf16 v[66:69], v[208:211], v[180:183], v[66:69]
	v_mfma_f32_16x16x32_bf16 v[114:117], v[192:195], v[160:163], v[114:117]
	v_mfma_f32_16x16x32_bf16 v[110:113], v[212:215], v[160:163], v[110:113]
	v_mfma_f32_16x16x32_bf16 v[98:101], v[192:195], v[168:171], v[98:101]
	v_mfma_f32_16x16x32_bf16 v[94:97], v[212:215], v[168:171], v[94:97]
	v_mfma_f32_16x16x32_bf16 v[82:85], v[192:195], v[176:179], v[82:85]
	v_mfma_f32_16x16x32_bf16 v[78:81], v[212:215], v[176:179], v[78:81]
	v_mfma_f32_16x16x32_bf16 v[70:73], v[192:195], v[184:187], v[70:73]
	v_mfma_f32_16x16x32_bf16 v[66:69], v[212:215], v[184:187], v[66:69]
	s_mov_b32 m0, s57
	v_lshl_add_u64 v[196:197], v[218:219], 0, s[10:11]
	s_barrier
	ds_read_b128 v[152:155], v159 offset:49152
	ds_read_b128 v[160:163], v159 offset:50176
	ds_read_b128 v[164:167], v159 offset:51200
	ds_read_b128 v[168:171], v159 offset:52224
	ds_read_b128 v[172:175], v159 offset:53248
	ds_read_b128 v[176:179], v159 offset:54272
	ds_read_b128 v[180:183], v159 offset:55296
	ds_read_b128 v[184:187], v159 offset:56320
	global_load_lds_dwordx4 v[196:197], off
	v_lshl_add_u64 v[196:197], v[220:221], 0, s[10:11]
	s_mov_b32 m0, s58
	s_nop 0
	global_load_lds_dwordx4 v[196:197], off
	s_barrier
	s_waitcnt lgkmcnt(0)
	s_waitcnt lgkmcnt(0)
	v_mfma_f32_16x16x32_bf16 v[62:65], v[130:133], v[152:155], v[62:65]
	v_mfma_f32_16x16x32_bf16 v[58:61], v[138:141], v[152:155], v[58:61]
	v_mfma_f32_16x16x32_bf16 v[54:57], v[130:133], v[164:167], v[54:57]
	v_mfma_f32_16x16x32_bf16 v[50:53], v[138:141], v[164:167], v[50:53]
	v_mfma_f32_16x16x32_bf16 v[46:49], v[130:133], v[172:175], v[46:49]
	v_mfma_f32_16x16x32_bf16 v[38:41], v[138:141], v[172:175], v[38:41]
	v_mfma_f32_16x16x32_bf16 v[30:33], v[130:133], v[180:183], v[30:33]
	v_mfma_f32_16x16x32_bf16 v[18:21], v[138:141], v[180:183], v[18:21]
	v_mfma_f32_16x16x32_bf16 v[62:65], v[134:137], v[160:163], v[62:65]
	v_mfma_f32_16x16x32_bf16 v[58:61], v[148:151], v[160:163], v[58:61]
	v_mfma_f32_16x16x32_bf16 v[54:57], v[134:137], v[168:171], v[54:57]
	v_mfma_f32_16x16x32_bf16 v[50:53], v[148:151], v[168:171], v[50:53]
	v_mfma_f32_16x16x32_bf16 v[46:49], v[134:137], v[176:179], v[46:49]
	v_mfma_f32_16x16x32_bf16 v[38:41], v[148:151], v[176:179], v[38:41]
	v_mfma_f32_16x16x32_bf16 v[30:33], v[134:137], v[184:187], v[30:33]
	v_mfma_f32_16x16x32_bf16 v[18:21], v[148:151], v[184:187], v[18:21]
	s_barrier
	s_add_u32 s22, s42, 0x40080
	s_addc_u32 s23, s43, 0
	s_add_i32 s42, s48, s52
	v_lshl_add_u64 v[130:131], s[22:23], 0, v[16:17]
	s_mov_b32 m0, s42
	s_nop 0
	global_load_lds_dwordx4 v[130:131], off
	v_lshl_add_u64 v[130:131], s[22:23], 0, v[142:143]
	s_add_i32 m0, s42, 0x2000
	s_nop 0
	global_load_lds_dwordx4 v[130:131], off
	s_cmp_eq_u32 s82, 12
	s_cbranch_scc0 .Lvl_2
	s_waitcnt vmcnt(6)
.Lvl_2:
	s_waitcnt vmcnt(10)
	s_barrier
	v_mfma_f32_16x16x32_bf16 v[42:45], v[188:191], v[152:155], v[42:45]
	v_mfma_f32_16x16x32_bf16 v[34:37], v[208:211], v[152:155], v[34:37]
	v_mfma_f32_16x16x32_bf16 v[26:29], v[188:191], v[164:167], v[26:29]
	v_mfma_f32_16x16x32_bf16 v[22:25], v[208:211], v[164:167], v[22:25]
	v_mfma_f32_16x16x32_bf16 v[12:15], v[188:191], v[172:175], v[12:15]
	v_mfma_f32_16x16x32_bf16 v[8:11], v[208:211], v[172:175], v[8:11]
	v_mfma_f32_16x16x32_bf16 v[4:7], v[188:191], v[180:183], v[4:7]
	v_mfma_f32_16x16x32_bf16 v[0:3], v[208:211], v[180:183], v[0:3]
	v_mfma_f32_16x16x32_bf16 v[42:45], v[192:195], v[160:163], v[42:45]
	v_mfma_f32_16x16x32_bf16 v[34:37], v[212:215], v[160:163], v[34:37]
	v_mfma_f32_16x16x32_bf16 v[26:29], v[192:195], v[168:171], v[26:29]
	v_mfma_f32_16x16x32_bf16 v[22:25], v[212:215], v[168:171], v[22:25]
	v_mfma_f32_16x16x32_bf16 v[12:15], v[192:195], v[176:179], v[12:15]
	v_mfma_f32_16x16x32_bf16 v[8:11], v[212:215], v[176:179], v[8:11]
	v_mfma_f32_16x16x32_bf16 v[4:7], v[192:195], v[184:187], v[4:7]
	v_mfma_f32_16x16x32_bf16 v[0:3], v[212:215], v[184:187], v[0:3]
	s_add_i32 s82, s82, 2
	s_add_u32 s61, s61, 0x100
	s_addc_u32 s79, s79, 0
	s_cmp_gt_u32 s82, 13
	s_mov_b64 s[22:23], s[40:41]
	s_barrier
	s_cbranch_scc0 .LBB0_174
	v_lshl_or_b32 v132, s2, 8, v158
	v_lshl_add_u32 v130, s18, 8, v156
	v_ashrrev_i32_e32 v133, 31, v132
	v_lshlrev_b64 v[148:149], 2, v[132:133]
	v_ashrrev_i32_e32 v131, 31, v130
	v_lshlrev_b64 v[152:153], 12, v[130:131]
	v_lshl_add_u64 v[150:151], s[20:21], 0, v[148:149]
	v_lshl_add_u64 v[154:155], v[150:151], 0, v[152:153]
	s_mov_b64 s[22:23], 0x10000
	v_lshl_add_u64 v[196:197], v[154:155], 0, s[22:23]
	s_mov_b64 s[22:23], 0x20000
	v_lshl_add_u64 v[224:225], v[154:155], 0, s[22:23]
	s_mov_b64 s[22:23], 0x30000
	v_lshl_add_u64 v[226:227], v[154:155], 0, s[22:23]
	s_mov_b64 s[22:23], 0x80000
	v_lshl_add_u64 v[240:241], v[154:155], 0, s[22:23]
	s_mov_b64 s[22:23], 0x90000
	v_lshl_add_u64 v[242:243], v[154:155], 0, s[22:23]
	s_mov_b64 s[22:23], 0xa0000
	v_lshl_add_u64 v[244:245], v[154:155], 0, s[22:23]
	s_mov_b64 s[22:23], 0xb0000
	v_lshl_add_u64 v[246:247], v[154:155], 0, s[22:23]
	global_load_dwordx4 v[160:163], v[154:155], off
	global_load_dwordx4 v[164:167], v[154:155], off offset:64
	global_load_dwordx4 v[168:171], v[154:155], off offset:512
	global_load_dwordx4 v[172:175], v[154:155], off offset:576
	global_load_dwordx4 v[176:179], v[196:197], off
	global_load_dwordx4 v[180:183], v[196:197], off offset:64
	global_load_dwordx4 v[184:187], v[196:197], off offset:512
	global_load_dwordx4 v[188:191], v[196:197], off offset:576
	global_load_dwordx4 v[192:195], v[224:225], off
	global_load_dwordx4 v[208:211], v[224:225], off offset:64
	global_load_dwordx4 v[212:215], v[224:225], off offset:512
	global_load_dwordx4 v[216:219], v[224:225], off offset:576
	global_load_dwordx4 v[220:223], v[226:227], off
	global_load_dwordx4 v[138:141], v[226:227], off offset:64
	global_load_dwordx4 v[134:137], v[226:227], off offset:512
	global_load_dwordx4 v[130:133], v[226:227], off offset:576
	s_waitcnt vmcnt(12)
	v_pk_add_f32 v[126:127], v[126:127], v[160:161]
	v_pk_add_f32 v[128:129], v[128:129], v[162:163]
	v_pk_add_f32 v[122:123], v[122:123], v[164:165]
	v_pk_add_f32 v[124:125], v[124:125], v[166:167]
	v_pk_add_f32 v[114:115], v[114:115], v[168:169]
	v_pk_add_f32 v[116:117], v[116:117], v[170:171]
	v_pk_add_f32 v[110:111], v[110:111], v[172:173]
	v_pk_add_f32 v[112:113], v[112:113], v[174:175]
	s_waitcnt vmcnt(8)
	v_pk_add_f32 v[118:119], v[118:119], v[176:177]
	v_pk_add_f32 v[120:121], v[120:121], v[178:179]
	v_pk_add_f32 v[106:107], v[106:107], v[180:181]
	v_pk_add_f32 v[108:109], v[108:109], v[182:183]
	v_pk_add_f32 v[98:99], v[98:99], v[184:185]
	v_pk_add_f32 v[100:101], v[100:101], v[186:187]
	v_pk_add_f32 v[94:95], v[94:95], v[188:189]
	v_pk_add_f32 v[96:97], v[96:97], v[190:191]
	s_waitcnt vmcnt(4)
	v_pk_add_f32 v[102:103], v[102:103], v[192:193]
	v_pk_add_f32 v[104:105], v[104:105], v[194:195]
	v_pk_add_f32 v[90:91], v[90:91], v[208:209]
	v_pk_add_f32 v[92:93], v[92:93], v[210:211]
	v_pk_add_f32 v[82:83], v[82:83], v[212:213]
	v_pk_add_f32 v[84:85], v[84:85], v[214:215]
	v_pk_add_f32 v[78:79], v[78:79], v[216:217]
	v_pk_add_f32 v[80:81], v[80:81], v[218:219]
	s_waitcnt vmcnt(0)
	v_pk_add_f32 v[86:87], v[86:87], v[220:221]
	v_pk_add_f32 v[88:89], v[88:89], v[222:223]
	v_pk_add_f32 v[74:75], v[74:75], v[138:139]
	v_pk_add_f32 v[76:77], v[76:77], v[140:141]
	v_pk_add_f32 v[70:71], v[70:71], v[134:135]
	v_pk_add_f32 v[72:73], v[72:73], v[136:137]
	v_pk_add_f32 v[66:67], v[66:67], v[130:131]
	v_pk_add_f32 v[68:69], v[68:69], v[132:133]
	global_load_dwordx4 v[160:163], v[240:241], off
	global_load_dwordx4 v[164:167], v[240:241], off offset:64
	global_load_dwordx4 v[168:171], v[240:241], off offset:512
	global_load_dwordx4 v[172:175], v[240:241], off offset:576
	global_load_dwordx4 v[176:179], v[242:243], off
	global_load_dwordx4 v[180:183], v[242:243], off offset:64
	global_load_dwordx4 v[184:187], v[242:243], off offset:512
	global_load_dwordx4 v[188:191], v[242:243], off offset:576
	global_load_dwordx4 v[192:195], v[244:245], off
	global_load_dwordx4 v[208:211], v[244:245], off offset:64
	global_load_dwordx4 v[212:215], v[244:245], off offset:512
	global_load_dwordx4 v[216:219], v[244:245], off offset:576
	global_load_dwordx4 v[220:223], v[246:247], off
	global_load_dwordx4 v[138:141], v[246:247], off offset:64
	global_load_dwordx4 v[134:137], v[246:247], off offset:512
	global_load_dwordx4 v[130:133], v[246:247], off offset:576
	global_store_dwordx4 v[154:155], v[126:129], off
	global_store_dwordx4 v[154:155], v[122:125], off offset:64
	global_store_dwordx4 v[154:155], v[114:117], off offset:512
	global_store_dwordx4 v[154:155], v[110:113], off offset:576
	global_store_dwordx4 v[196:197], v[118:121], off
	global_store_dwordx4 v[196:197], v[106:109], off offset:64
	global_store_dwordx4 v[196:197], v[98:101], off offset:512
	global_store_dwordx4 v[196:197], v[94:97], off offset:576
	global_store_dwordx4 v[224:225], v[102:105], off
	global_store_dwordx4 v[224:225], v[90:93], off offset:64
	global_store_dwordx4 v[224:225], v[82:85], off offset:512
	global_store_dwordx4 v[224:225], v[78:81], off offset:576
	global_store_dwordx4 v[226:227], v[86:89], off
	global_store_dwordx4 v[226:227], v[74:77], off offset:64
	global_store_dwordx4 v[226:227], v[70:73], off offset:512
	global_store_dwordx4 v[226:227], v[66:69], off offset:576
	s_waitcnt vmcnt(0)
	v_pk_add_f32 v[62:63], v[62:63], v[160:161]
	v_pk_add_f32 v[64:65], v[64:65], v[162:163]
	v_pk_add_f32 v[58:59], v[58:59], v[164:165]
	v_pk_add_f32 v[60:61], v[60:61], v[166:167]
	v_pk_add_f32 v[42:43], v[42:43], v[168:169]
	v_pk_add_f32 v[44:45], v[44:45], v[170:171]
	v_pk_add_f32 v[34:35], v[34:35], v[172:173]
	v_pk_add_f32 v[36:37], v[36:37], v[174:175]
	v_pk_add_f32 v[54:55], v[54:55], v[176:177]
	v_pk_add_f32 v[56:57], v[56:57], v[178:179]
	v_pk_add_f32 v[50:51], v[50:51], v[180:181]
	v_pk_add_f32 v[52:53], v[52:53], v[182:183]
	v_pk_add_f32 v[26:27], v[26:27], v[184:185]
	v_pk_add_f32 v[28:29], v[28:29], v[186:187]
	v_pk_add_f32 v[22:23], v[22:23], v[188:189]
	v_pk_add_f32 v[24:25], v[24:25], v[190:191]
	v_pk_add_f32 v[46:47], v[46:47], v[192:193]
	v_pk_add_f32 v[48:49], v[48:49], v[194:195]
	v_pk_add_f32 v[38:39], v[38:39], v[208:209]
	v_pk_add_f32 v[40:41], v[40:41], v[210:211]
	v_pk_add_f32 v[12:13], v[12:13], v[212:213]
	v_pk_add_f32 v[14:15], v[14:15], v[214:215]
	v_pk_add_f32 v[8:9], v[8:9], v[216:217]
	v_pk_add_f32 v[10:11], v[10:11], v[218:219]
	v_pk_add_f32 v[30:31], v[30:31], v[220:221]
	v_pk_add_f32 v[32:33], v[32:33], v[222:223]
	v_pk_add_f32 v[18:19], v[18:19], v[138:139]
	v_pk_add_f32 v[20:21], v[20:21], v[140:141]
	v_pk_add_f32 v[4:5], v[4:5], v[134:135]
	v_pk_add_f32 v[6:7], v[6:7], v[136:137]
	v_pk_add_f32 v[0:1], v[0:1], v[130:131]
	v_pk_add_f32 v[2:3], v[2:3], v[132:133]
	global_store_dwordx4 v[240:241], v[62:65], off
	global_store_dwordx4 v[240:241], v[58:61], off offset:64
	global_store_dwordx4 v[240:241], v[42:45], off offset:512
	global_store_dwordx4 v[240:241], v[34:37], off offset:576
	global_store_dwordx4 v[242:243], v[54:57], off
	global_store_dwordx4 v[242:243], v[50:53], off offset:64
	global_store_dwordx4 v[242:243], v[26:29], off offset:512
	global_store_dwordx4 v[242:243], v[22:25], off offset:576
	global_store_dwordx4 v[244:245], v[46:49], off
	global_store_dwordx4 v[244:245], v[38:41], off offset:64
	global_store_dwordx4 v[244:245], v[12:15], off offset:512
	global_store_dwordx4 v[244:245], v[8:11], off offset:576
	global_store_dwordx4 v[246:247], v[30:33], off
	global_store_dwordx4 v[246:247], v[18:21], off offset:64
	global_store_dwordx4 v[246:247], v[4:7], off offset:512
	global_store_dwordx4 v[246:247], v[0:3], off offset:576
	v_readlane_b32 s82, v255, 5
	s_and_b64 vcc, exec, s[38:39]
	s_mov_b32 s2, s4
	s_mov_b32 s18, s8
	s_mov_b64 s[40:41], s[16:17]
	s_mov_b64 s[22:23], s[14:15]
	v_readlane_b32 s83, v255, 6
	s_cbranch_vccz .LBB0_167
	s_waitcnt vmcnt(0)
	s_cmpk_gt_u32 s35, 0xff
	s_cbranch_scc1 .LBB0_178
	s_barrier

.LBB0_211:
	s_add_u32 s18, s16, 0xfffe0080
	s_addc_u32 s19, s17, -1
	s_add_i32 s42, 0, 0x10000
	v_add_u32_e32 v12, s42, v241
	ds_read_b128 v[0:3], v12
	ds_read_b128 v[4:7], v12 offset:1024
	ds_read_b128 v[8:11], v12 offset:2048
	ds_read_b128 v[12:15], v12 offset:3072
	s_cmp_eq_u32 s41, 4
	s_cselect_b32 s23, s2, s19
	s_cselect_b32 s22, s9, s18
	s_cselect_b32 s19, s12, s40
	s_cselect_b32 s18, s15, s34
	v_lshl_add_u64 v[178:179], s[16:17], 0, v[216:217]
	s_add_i32 m0, s52, 0xc000
	ds_read_b128 v[146:149], v243
	ds_read_b128 v[150:153], v243 offset:1024
	ds_read_b128 v[154:157], v243 offset:2048
	ds_read_b128 v[158:161], v243 offset:3072
	ds_read_b128 v[162:165], v243 offset:4096
	ds_read_b128 v[166:169], v243 offset:5120
	ds_read_b128 v[170:173], v243 offset:6144
	ds_read_b128 v[174:177], v243 offset:7168
	global_load_lds_dwordx4 v[178:179], off
	v_lshl_add_u64 v[178:179], s[16:17], 0, v[214:215]
	s_add_i32 m0, s52, 0xe000
	s_nop 0
	global_load_lds_dwordx4 v[178:179], off
	s_waitcnt lgkmcnt(8)
	s_cmp_eq_u32 s41, -2
	s_cbranch_scc1 .Lvw_3_1
	s_waitcnt vmcnt(10)
.Lvw_3_1:
	s_barrier
	s_waitcnt lgkmcnt(0)
	s_waitcnt lgkmcnt(0)
	v_mfma_f32_16x16x32_bf16 v[142:145], v[0:3], v[146:149], v[142:145]
	v_mfma_f32_16x16x32_bf16 v[138:141], v[8:11], v[146:149], v[138:141]
	v_mfma_f32_16x16x32_bf16 v[134:137], v[0:3], v[154:157], v[134:137]
	v_mfma_f32_16x16x32_bf16 v[130:133], v[8:11], v[154:157], v[130:133]
	v_mfma_f32_16x16x32_bf16 v[126:129], v[0:3], v[162:165], v[126:129]
	v_mfma_f32_16x16x32_bf16 v[122:125], v[8:11], v[162:165], v[122:125]
	v_mfma_f32_16x16x32_bf16 v[118:121], v[0:3], v[170:173], v[118:121]
	v_mfma_f32_16x16x32_bf16 v[114:117], v[8:11], v[170:173], v[114:117]
	v_mfma_f32_16x16x32_bf16 v[142:145], v[4:7], v[150:153], v[142:145]
	v_mfma_f32_16x16x32_bf16 v[138:141], v[12:15], v[150:153], v[138:141]
	v_mfma_f32_16x16x32_bf16 v[134:137], v[4:7], v[158:161], v[134:137]
	v_mfma_f32_16x16x32_bf16 v[130:133], v[12:15], v[158:161], v[130:133]
	v_mfma_f32_16x16x32_bf16 v[126:129], v[4:7], v[166:169], v[126:129]
	v_mfma_f32_16x16x32_bf16 v[122:125], v[12:15], v[166:169], v[122:125]
	v_mfma_f32_16x16x32_bf16 v[118:121], v[4:7], v[174:177], v[118:121]
	v_mfma_f32_16x16x32_bf16 v[114:117], v[12:15], v[174:177], v[114:117]
	s_barrier
	s_add_i32 s55, 0, 0x14000
	s_add_i32 s42, s42, s49
	v_add_u32_e32 v190, s55, v241
	v_lshl_add_u64 v[194:195], s[18:19], 0, v[16:17]
	s_mov_b32 m0, s42
	ds_read_b128 v[178:181], v190
	ds_read_b128 v[182:185], v190 offset:1024
	ds_read_b128 v[186:189], v190 offset:2048
	ds_read_b128 v[190:193], v190 offset:3072
	global_load_lds_dwordx4 v[194:195], off
	v_lshl_add_u64 v[196:197], s[18:19], 0, v[212:213]
	s_add_i32 m0, s42, 0x2000
	s_nop 0
	global_load_lds_dwordx4 v[196:197], off
	s_cmp_eq_u32 s41, -2
	s_cbranch_scc1 .Lvw_3_2
	s_waitcnt vmcnt(10)
.Lvw_3_2:
	s_barrier
	s_waitcnt lgkmcnt(0)
	s_waitcnt lgkmcnt(0)
	v_mfma_f32_16x16x32_bf16 v[110:113], v[178:181], v[146:149], v[110:113]
	v_mfma_f32_16x16x32_bf16 v[106:109], v[186:189], v[146:149], v[106:109]
	v_mfma_f32_16x16x32_bf16 v[102:105], v[178:181], v[154:157], v[102:105]
	v_mfma_f32_16x16x32_bf16 v[98:101], v[186:189], v[154:157], v[98:101]
	v_mfma_f32_16x16x32_bf16 v[94:97], v[178:181], v[162:165], v[94:97]
	v_mfma_f32_16x16x32_bf16 v[90:93], v[186:189], v[162:165], v[90:93]
	v_mfma_f32_16x16x32_bf16 v[86:89], v[178:181], v[170:173], v[86:89]
	v_mfma_f32_16x16x32_bf16 v[82:85], v[186:189], v[170:173], v[82:85]
	v_mfma_f32_16x16x32_bf16 v[110:113], v[182:185], v[150:153], v[110:113]
	v_mfma_f32_16x16x32_bf16 v[106:109], v[190:193], v[150:153], v[106:109]
	v_mfma_f32_16x16x32_bf16 v[102:105], v[182:185], v[158:161], v[102:105]
	v_mfma_f32_16x16x32_bf16 v[98:101], v[190:193], v[158:161], v[98:101]
	v_mfma_f32_16x16x32_bf16 v[94:97], v[182:185], v[166:169], v[94:97]
	v_mfma_f32_16x16x32_bf16 v[90:93], v[190:193], v[166:169], v[90:93]
	v_mfma_f32_16x16x32_bf16 v[86:89], v[182:185], v[174:177], v[86:89]
	v_mfma_f32_16x16x32_bf16 v[82:85], v[190:193], v[174:177], v[82:85]
	s_mov_b32 m0, s52
	v_lshl_add_u64 v[218:219], s[22:23], 0, v[208:209]
	s_barrier
	ds_read_b128 v[146:149], v243 offset:16384
	ds_read_b128 v[150:153], v243 offset:17408
	ds_read_b128 v[154:157], v243 offset:18432
	ds_read_b128 v[158:161], v243 offset:19456
	ds_read_b128 v[162:165], v243 offset:20480
	ds_read_b128 v[166:169], v243 offset:21504
	ds_read_b128 v[170:173], v243 offset:22528
	ds_read_b128 v[174:177], v243 offset:23552
	global_load_lds_dwordx4 v[218:219], off
	v_lshl_add_u64 v[220:221], s[22:23], 0, v[210:211]
	s_mov_b32 m0, s58
	s_nop 0
	global_load_lds_dwordx4 v[220:221], off
	s_barrier
	s_waitcnt lgkmcnt(0)
	s_waitcnt lgkmcnt(0)
	v_mfma_f32_16x16x32_bf16 v[78:81], v[0:3], v[146:149], v[78:81]
	v_mfma_f32_16x16x32_bf16 v[74:77], v[8:11], v[146:149], v[74:77]
	v_mfma_f32_16x16x32_bf16 v[70:73], v[0:3], v[154:157], v[70:73]
	v_mfma_f32_16x16x32_bf16 v[66:69], v[8:11], v[154:157], v[66:69]
	v_mfma_f32_16x16x32_bf16 v[62:65], v[0:3], v[162:165], v[62:65]
	v_mfma_f32_16x16x32_bf16 v[58:61], v[8:11], v[162:165], v[58:61]
	v_mfma_f32_16x16x32_bf16 v[0:3], v[0:3], v[170:173], v[54:57]
	v_mfma_f32_16x16x32_bf16 v[78:81], v[4:7], v[150:153], v[78:81]
	v_mfma_f32_16x16x32_bf16 v[74:77], v[12:15], v[150:153], v[74:77]
	v_mfma_f32_16x16x32_bf16 v[70:73], v[4:7], v[158:161], v[70:73]
	v_mfma_f32_16x16x32_bf16 v[66:69], v[12:15], v[158:161], v[66:69]
	v_mfma_f32_16x16x32_bf16 v[62:65], v[4:7], v[166:169], v[62:65]
	v_mfma_f32_16x16x32_bf16 v[58:61], v[12:15], v[166:169], v[58:61]
	v_mfma_f32_16x16x32_bf16 v[0:3], v[4:7], v[174:177], v[0:3]
	v_mfma_f32_16x16x32_bf16 v[4:7], v[8:11], v[170:173], v[50:53]
	v_mfma_f32_16x16x32_bf16 v[4:7], v[12:15], v[174:177], v[4:7]
	s_barrier
	s_add_u32 s42, s18, 0x20000
	s_addc_u32 s43, s19, 0
	s_add_i32 s55, s55, s49
	v_lshl_add_u64 v[8:9], s[42:43], 0, v[16:17]
	s_mov_b32 m0, s55
	s_nop 0
	global_load_lds_dwordx4 v[8:9], off
	v_lshl_add_u64 v[8:9], s[42:43], 0, v[212:213]
	s_add_i32 m0, s55, 0x2000
	s_nop 0
	global_load_lds_dwordx4 v[8:9], off
	s_waitcnt vmcnt(10)
	s_barrier
	v_mfma_f32_16x16x32_bf16 v[38:41], v[178:181], v[154:157], v[38:41]
	v_mfma_f32_16x16x32_bf16 v[34:37], v[186:189], v[154:157], v[34:37]
	v_mfma_f32_16x16x32_bf16 v[30:33], v[178:181], v[162:165], v[30:33]
	v_mfma_f32_16x16x32_bf16 v[26:29], v[186:189], v[162:165], v[26:29]
	v_mfma_f32_16x16x32_bf16 v[22:25], v[178:181], v[170:173], v[22:25]
	v_mfma_f32_16x16x32_bf16 v[18:21], v[186:189], v[170:173], v[18:21]
	v_mfma_f32_16x16x32_bf16 v[8:11], v[178:181], v[146:149], v[46:49]
	v_mfma_f32_16x16x32_bf16 v[12:15], v[186:189], v[146:149], v[42:45]
	v_mfma_f32_16x16x32_bf16 v[38:41], v[182:185], v[158:161], v[38:41]
	v_mfma_f32_16x16x32_bf16 v[34:37], v[190:193], v[158:161], v[34:37]
	v_mfma_f32_16x16x32_bf16 v[30:33], v[182:185], v[166:169], v[30:33]
	v_mfma_f32_16x16x32_bf16 v[26:29], v[190:193], v[166:169], v[26:29]
	v_mfma_f32_16x16x32_bf16 v[22:25], v[182:185], v[174:177], v[22:25]
	v_mfma_f32_16x16x32_bf16 v[18:21], v[190:193], v[174:177], v[18:21]
	v_mfma_f32_16x16x32_bf16 v[8:11], v[182:185], v[150:153], v[8:11]
	v_mfma_f32_16x16x32_bf16 v[12:15], v[190:193], v[150:153], v[12:15]
	s_add_i32 s42, 0, 0x18000
	v_add_u32_e32 v54, s42, v241
	s_barrier
	ds_read_b128 v[42:45], v54
	ds_read_b128 v[46:49], v54 offset:1024
	ds_read_b128 v[50:53], v54 offset:2048
	ds_read_b128 v[146:149], v54 offset:3072
	s_add_u32 s22, s22, 0x20000
	s_addc_u32 s23, s23, 0
	s_mov_b32 m0, s59
	v_lshl_add_u64 v[178:179], s[22:23], 0, v[208:209]
	ds_read_b128 v[54:57], v243 offset:32768
	ds_read_b128 v[150:153], v243 offset:33792
	ds_read_b128 v[154:157], v243 offset:34816
	ds_read_b128 v[158:161], v243 offset:35840
	ds_read_b128 v[162:165], v243 offset:36864
	ds_read_b128 v[166:169], v243 offset:37888
	ds_read_b128 v[170:173], v243 offset:38912
	ds_read_b128 v[174:177], v243 offset:39936
	global_load_lds_dwordx4 v[178:179], off
	v_lshl_add_u64 v[178:179], s[22:23], 0, v[210:211]
	s_mov_b32 m0, s60
	s_nop 0
	global_load_lds_dwordx4 v[178:179], off
	s_waitcnt lgkmcnt(8)
	s_waitcnt vmcnt(10)
	s_barrier
	s_waitcnt lgkmcnt(0)
	s_waitcnt lgkmcnt(0)
	v_mfma_f32_16x16x32_bf16 v[142:145], v[42:45], v[54:57], v[142:145]
	v_mfma_f32_16x16x32_bf16 v[138:141], v[50:53], v[54:57], v[138:141]
	v_mfma_f32_16x16x32_bf16 v[134:137], v[42:45], v[154:157], v[134:137]
	v_mfma_f32_16x16x32_bf16 v[130:133], v[50:53], v[154:157], v[130:133]
	v_mfma_f32_16x16x32_bf16 v[126:129], v[42:45], v[162:165], v[126:129]
	v_mfma_f32_16x16x32_bf16 v[122:125], v[50:53], v[162:165], v[122:125]
	v_mfma_f32_16x16x32_bf16 v[118:121], v[42:45], v[170:173], v[118:121]
	v_mfma_f32_16x16x32_bf16 v[114:117], v[50:53], v[170:173], v[114:117]
	v_mfma_f32_16x16x32_bf16 v[142:145], v[46:49], v[150:153], v[142:145]
	v_mfma_f32_16x16x32_bf16 v[138:141], v[146:149], v[150:153], v[138:141]
	v_mfma_f32_16x16x32_bf16 v[134:137], v[46:49], v[158:161], v[134:137]
	v_mfma_f32_16x16x32_bf16 v[130:133], v[146:149], v[158:161], v[130:133]
	v_mfma_f32_16x16x32_bf16 v[126:129], v[46:49], v[166:169], v[126:129]
	v_mfma_f32_16x16x32_bf16 v[122:125], v[146:149], v[166:169], v[122:125]
	v_mfma_f32_16x16x32_bf16 v[118:121], v[46:49], v[174:177], v[118:121]
	v_mfma_f32_16x16x32_bf16 v[114:117], v[146:149], v[174:177], v[114:117]
	s_barrier
	s_add_i32 s22, 0, 0x1c000
	s_add_i32 s23, s42, s49
	v_add_u32_e32 v190, s22, v241
	v_lshl_add_u64 v[194:195], v[194:195], 0, s[10:11]
	s_mov_b32 m0, s23
	ds_read_b128 v[178:181], v190
	ds_read_b128 v[182:185], v190 offset:1024
	ds_read_b128 v[186:189], v190 offset:2048
	ds_read_b128 v[190:193], v190 offset:3072
	global_load_lds_dwordx4 v[194:195], off
	v_lshl_add_u64 v[194:195], v[196:197], 0, s[10:11]
	s_add_i32 m0, s23, 0x2000
	s_nop 0
	global_load_lds_dwordx4 v[194:195], off
	s_waitcnt vmcnt(10)
	s_barrier
	s_waitcnt lgkmcnt(0)
	s_waitcnt lgkmcnt(0)
	v_mfma_f32_16x16x32_bf16 v[110:113], v[178:181], v[54:57], v[110:113]
	v_mfma_f32_16x16x32_bf16 v[54:57], v[186:189], v[54:57], v[106:109]
	v_mfma_f32_16x16x32_bf16 v[106:109], v[190:193], v[150:153], v[54:57]
	v_mfma_f32_16x16x32_bf16 v[54:57], v[178:181], v[154:157], v[102:105]
	v_mfma_f32_16x16x32_bf16 v[102:105], v[182:185], v[158:161], v[54:57]
	v_mfma_f32_16x16x32_bf16 v[54:57], v[186:189], v[154:157], v[98:101]
	v_mfma_f32_16x16x32_bf16 v[98:101], v[190:193], v[158:161], v[54:57]
	v_mfma_f32_16x16x32_bf16 v[54:57], v[178:181], v[162:165], v[94:97]
	v_mfma_f32_16x16x32_bf16 v[94:97], v[182:185], v[166:169], v[54:57]
	v_mfma_f32_16x16x32_bf16 v[54:57], v[186:189], v[162:165], v[90:93]
	v_mfma_f32_16x16x32_bf16 v[90:93], v[190:193], v[166:169], v[54:57]
	v_mfma_f32_16x16x32_bf16 v[54:57], v[178:181], v[170:173], v[86:89]
	v_mfma_f32_16x16x32_bf16 v[86:89], v[182:185], v[174:177], v[54:57]
	v_mfma_f32_16x16x32_bf16 v[54:57], v[186:189], v[170:173], v[82:85]
	v_mfma_f32_16x16x32_bf16 v[110:113], v[182:185], v[150:153], v[110:113]
	v_mfma_f32_16x16x32_bf16 v[82:85], v[190:193], v[174:177], v[54:57]
	s_mov_b32 m0, s61
	s_nop 3
	v_lshl_add_u64 v[54:55], v[218:219], 0, s[10:11]
	s_barrier
	ds_read_b128 v[150:153], v243 offset:49152
	ds_read_b128 v[154:157], v243 offset:50176
	ds_read_b128 v[158:161], v243 offset:51200
	ds_read_b128 v[162:165], v243 offset:52224
	ds_read_b128 v[166:169], v243 offset:53248
	ds_read_b128 v[170:173], v243 offset:54272
	ds_read_b128 v[174:177], v243 offset:55296
	ds_read_b128 v[194:197], v243 offset:56320
	global_load_lds_dwordx4 v[54:55], off
	v_lshl_add_u64 v[54:55], v[220:221], 0, s[10:11]
	s_mov_b32 m0, s35
	s_nop 0
	global_load_lds_dwordx4 v[54:55], off
	s_barrier
	s_waitcnt lgkmcnt(0)
	s_waitcnt lgkmcnt(0)
	v_mfma_f32_16x16x32_bf16 v[54:57], v[42:45], v[150:153], v[78:81]
	v_mfma_f32_16x16x32_bf16 v[78:81], v[46:49], v[154:157], v[54:57]
	v_mfma_f32_16x16x32_bf16 v[54:57], v[50:53], v[150:153], v[74:77]
	v_mfma_f32_16x16x32_bf16 v[74:77], v[146:149], v[154:157], v[54:57]
	v_mfma_f32_16x16x32_bf16 v[54:57], v[42:45], v[158:161], v[70:73]
	v_mfma_f32_16x16x32_bf16 v[70:73], v[46:49], v[162:165], v[54:57]
	v_mfma_f32_16x16x32_bf16 v[54:57], v[50:53], v[158:161], v[66:69]
	v_mfma_f32_16x16x32_bf16 v[66:69], v[146:149], v[162:165], v[54:57]
	v_mfma_f32_16x16x32_bf16 v[54:57], v[42:45], v[166:169], v[62:65]
	v_mfma_f32_16x16x32_bf16 v[62:65], v[46:49], v[170:173], v[54:57]
	v_mfma_f32_16x16x32_bf16 v[54:57], v[50:53], v[166:169], v[58:61]
	v_mfma_f32_16x16x32_bf16 v[0:3], v[42:45], v[174:177], v[0:3]
	v_mfma_f32_16x16x32_bf16 v[58:61], v[146:149], v[170:173], v[54:57]
	v_mfma_f32_16x16x32_bf16 v[54:57], v[46:49], v[194:197], v[0:3]
	v_mfma_f32_16x16x32_bf16 v[0:3], v[50:53], v[174:177], v[4:7]
	v_mfma_f32_16x16x32_bf16 v[50:53], v[146:149], v[194:197], v[0:3]
	s_barrier
	s_add_u32 s18, s18, 0x20080
	s_addc_u32 s19, s19, 0
	s_add_i32 s22, s22, s49
	s_nop 1
	v_lshl_add_u64 v[0:1], s[18:19], 0, v[16:17]
	s_mov_b32 m0, s22
	s_nop 0
	global_load_lds_dwordx4 v[0:1], off
	v_lshl_add_u64 v[0:1], s[18:19], 0, v[212:213]
	s_add_i32 m0, s22, 0x2000
	s_nop 0
	global_load_lds_dwordx4 v[0:1], off
	s_cmp_eq_u32 s41, 4
	s_cbranch_scc0 .Lvl_3
	s_waitcnt vmcnt(6)
.Lvl_3:
	s_waitcnt vmcnt(10)
	s_barrier
	v_mfma_f32_16x16x32_bf16 v[0:3], v[178:181], v[150:153], v[8:11]
	v_mfma_f32_16x16x32_bf16 v[46:49], v[182:185], v[154:157], v[0:3]
	v_mfma_f32_16x16x32_bf16 v[0:3], v[186:189], v[150:153], v[12:15]
	v_mfma_f32_16x16x32_bf16 v[42:45], v[190:193], v[154:157], v[0:3]
	v_mfma_f32_16x16x32_bf16 v[0:3], v[178:181], v[158:161], v[38:41]
	v_mfma_f32_16x16x32_bf16 v[38:41], v[182:185], v[162:165], v[0:3]
	v_mfma_f32_16x16x32_bf16 v[0:3], v[186:189], v[158:161], v[34:37]
	v_mfma_f32_16x16x32_bf16 v[34:37], v[190:193], v[162:165], v[0:3]
	v_mfma_f32_16x16x32_bf16 v[0:3], v[178:181], v[166:169], v[30:33]
	v_mfma_f32_16x16x32_bf16 v[30:33], v[182:185], v[170:173], v[0:3]
	v_mfma_f32_16x16x32_bf16 v[0:3], v[186:189], v[166:169], v[26:29]
	v_mfma_f32_16x16x32_bf16 v[26:29], v[190:193], v[170:173], v[0:3]
	v_mfma_f32_16x16x32_bf16 v[0:3], v[178:181], v[174:177], v[22:25]
	v_mfma_f32_16x16x32_bf16 v[22:25], v[182:185], v[194:197], v[0:3]
	v_mfma_f32_16x16x32_bf16 v[0:3], v[186:189], v[174:177], v[18:21]
	v_mfma_f32_16x16x32_bf16 v[18:21], v[190:193], v[194:197], v[0:3]
	s_add_i32 s41, s41, 2
	s_add_u32 s34, s34, 0x100
	s_addc_u32 s40, s40, 0
	s_add_u32 s16, s16, 0x100
	s_addc_u32 s17, s17, 0
	s_cmp_gt_u32 s41, 5
	s_barrier
	s_cbranch_scc0 .LBB0_211
	s_cmp_eq_u32 s84, 3
	s_cselect_b64 s[16:17], -1, 0
	s_cmp_lg_u32 s84, 3
	v_lshl_add_u32 v220, s8, 8, v240
	v_lshl_or_b32 v218, s14, 8, v242
	s_cselect_b64 s[8:9], -1, 0
	s_lshl_b32 s14, s84, 10
	v_mov_b64_e32 v[0:1], s[94:95]
	s_ashr_i32 s15, s14, 31
	v_mad_i64_i32 v[0:1], s[18:19], v220, s66, v[0:1]
	v_ashrrev_i32_e32 v219, 31, v218
	v_lshl_add_u64 v[0:1], s[14:15], 1, v[0:1]
	v_lshl_add_u64 v[4:5], v[218:219], 1, v[0:1]
	v_add_co_u32_e32 v0, vcc, 0x2000, v4
	s_mov_b64 s[18:19], 0x2400
	s_nop 0
	v_addc_co_u32_e32 v1, vcc, 0, v5, vcc
	global_load_dwordx4 v[0:3], v[0:1], off offset:1024
	s_and_b64 vcc, exec, s[16:17]
	v_lshl_add_u64 v[4:5], v[4:5], 0, s[18:19]
	s_cbranch_vccnz .LBB0_214
	global_load_dwordx4 v[12:15], v[4:5], off offset:2048

.LBB0_979:
	s_add_u32 s22, s20, 0xfffc0080
	s_addc_u32 s23, s21, -1
	s_add_i32 s61, 0, 0x10000
	v_add_u32_e32 v144, s61, v147
	ds_read_b128 v[140:143], v144
	ds_read_b128 v[150:153], v144 offset:1024
	ds_read_b128 v[154:157], v144 offset:2048
	ds_read_b128 v[158:161], v144 offset:3072
	s_cmp_eq_u32 s60, 12
	s_cselect_b32 s29, s9, s23
	s_cselect_b32 s28, s56, s22
	s_cselect_b32 s23, s5, s59
	s_cselect_b32 s22, s57, s58
	v_lshl_add_u64 v[144:145], s[20:21], 0, v[138:139]
	s_add_i32 m0, s12, 0xc000
	ds_read_b128 v[162:165], v149
	ds_read_b128 v[166:169], v149 offset:1024
	ds_read_b128 v[170:173], v149 offset:2048
	ds_read_b128 v[174:177], v149 offset:3072
	ds_read_b128 v[178:181], v149 offset:4096
	ds_read_b128 v[182:185], v149 offset:5120
	ds_read_b128 v[186:189], v149 offset:6144
	ds_read_b128 v[190:193], v149 offset:7168
	global_load_lds_dwordx4 v[144:145], off
	v_lshl_add_u64 v[144:145], s[20:21], 0, v[136:137]
	s_add_i32 m0, s12, 0xe000
	s_nop 0
	global_load_lds_dwordx4 v[144:145], off
	s_waitcnt lgkmcnt(8)
	s_cmp_eq_u32 s60, -2
	s_cbranch_scc1 .Lvw_4_1
	s_waitcnt vmcnt(10)
.Lvw_4_1:
	s_barrier
	s_waitcnt lgkmcnt(0)
	s_waitcnt lgkmcnt(0)
	v_mfma_f32_16x16x32_bf16 v[78:81], v[140:143], v[162:165], v[78:81]
	v_mfma_f32_16x16x32_bf16 v[74:77], v[154:157], v[162:165], v[74:77]
	v_mfma_f32_16x16x32_bf16 v[70:73], v[140:143], v[170:173], v[70:73]
	v_mfma_f32_16x16x32_bf16 v[66:69], v[154:157], v[170:173], v[66:69]
	v_mfma_f32_16x16x32_bf16 v[62:65], v[140:143], v[178:181], v[62:65]
	v_mfma_f32_16x16x32_bf16 v[54:57], v[154:157], v[178:181], v[54:57]
	v_mfma_f32_16x16x32_bf16 v[50:53], v[140:143], v[186:189], v[50:53]
	v_mfma_f32_16x16x32_bf16 v[42:45], v[154:157], v[186:189], v[42:45]
	v_mfma_f32_16x16x32_bf16 v[78:81], v[150:153], v[166:169], v[78:81]
	v_mfma_f32_16x16x32_bf16 v[74:77], v[158:161], v[166:169], v[74:77]
	v_mfma_f32_16x16x32_bf16 v[70:73], v[150:153], v[174:177], v[70:73]
	v_mfma_f32_16x16x32_bf16 v[66:69], v[158:161], v[174:177], v[66:69]
	v_mfma_f32_16x16x32_bf16 v[62:65], v[150:153], v[182:185], v[62:65]
	v_mfma_f32_16x16x32_bf16 v[54:57], v[158:161], v[182:185], v[54:57]
	v_mfma_f32_16x16x32_bf16 v[50:53], v[150:153], v[190:193], v[50:53]
	v_mfma_f32_16x16x32_bf16 v[42:45], v[158:161], v[190:193], v[42:45]
	s_barrier
	s_add_i32 s79, 0, 0x14000
	v_add_u32_e32 v144, s79, v147
	s_add_i32 s61, s61, s48
	ds_read_b128 v[194:197], v144
	ds_read_b128 v[208:211], v144 offset:1024
	ds_read_b128 v[212:215], v144 offset:2048
	ds_read_b128 v[216:219], v144 offset:3072
	v_lshl_add_u64 v[144:145], s[22:23], 0, v[16:17]
	s_mov_b32 m0, s61
	v_lshl_add_u64 v[220:221], s[22:23], 0, v[130:131]
	global_load_lds_dwordx4 v[144:145], off
	s_add_i32 m0, s61, 0x2000
	s_nop 0
	global_load_lds_dwordx4 v[220:221], off
	s_cmp_eq_u32 s60, -2
	s_cbranch_scc1 .Lvw_4_2
	s_waitcnt vmcnt(10)
.Lvw_4_2:
	s_barrier
	s_waitcnt lgkmcnt(0)
	s_waitcnt lgkmcnt(0)
	v_mfma_f32_16x16x32_bf16 v[126:129], v[194:197], v[162:165], v[126:129]
	v_mfma_f32_16x16x32_bf16 v[122:125], v[212:215], v[162:165], v[122:125]
	v_mfma_f32_16x16x32_bf16 v[118:121], v[194:197], v[170:173], v[118:121]
	v_mfma_f32_16x16x32_bf16 v[114:117], v[212:215], v[170:173], v[114:117]
	v_mfma_f32_16x16x32_bf16 v[110:113], v[194:197], v[178:181], v[110:113]
	v_mfma_f32_16x16x32_bf16 v[106:109], v[212:215], v[178:181], v[106:109]
	v_mfma_f32_16x16x32_bf16 v[102:105], v[194:197], v[186:189], v[102:105]
	v_mfma_f32_16x16x32_bf16 v[98:101], v[212:215], v[186:189], v[98:101]
	v_mfma_f32_16x16x32_bf16 v[126:129], v[208:211], v[166:169], v[126:129]
	v_mfma_f32_16x16x32_bf16 v[122:125], v[216:219], v[166:169], v[122:125]
	v_mfma_f32_16x16x32_bf16 v[118:121], v[208:211], v[174:177], v[118:121]
	v_mfma_f32_16x16x32_bf16 v[114:117], v[216:219], v[174:177], v[114:117]
	v_mfma_f32_16x16x32_bf16 v[110:113], v[208:211], v[182:185], v[110:113]
	v_mfma_f32_16x16x32_bf16 v[106:109], v[216:219], v[182:185], v[106:109]
	v_mfma_f32_16x16x32_bf16 v[102:105], v[208:211], v[190:193], v[102:105]
	v_mfma_f32_16x16x32_bf16 v[98:101], v[216:219], v[190:193], v[98:101]
	s_mov_b32 m0, s12
	v_lshl_add_u64 v[222:223], s[28:29], 0, v[134:135]
	s_barrier
	ds_read_b128 v[162:165], v149 offset:16384
	ds_read_b128 v[166:169], v149 offset:17408
	ds_read_b128 v[170:173], v149 offset:18432
	ds_read_b128 v[174:177], v149 offset:19456
	ds_read_b128 v[178:181], v149 offset:20480
	ds_read_b128 v[182:185], v149 offset:21504
	ds_read_b128 v[186:189], v149 offset:22528
	ds_read_b128 v[190:193], v149 offset:23552
	global_load_lds_dwordx4 v[222:223], off
	v_lshl_add_u64 v[224:225], s[28:29], 0, v[132:133]
	s_mov_b32 m0, s34
	s_nop 0
	global_load_lds_dwordx4 v[224:225], off
	s_barrier
	s_waitcnt lgkmcnt(0)
	s_waitcnt lgkmcnt(0)
	v_mfma_f32_16x16x32_bf16 v[34:37], v[140:143], v[162:165], v[34:37]
	v_mfma_f32_16x16x32_bf16 v[30:33], v[154:157], v[162:165], v[30:33]
	v_mfma_f32_16x16x32_bf16 v[22:25], v[140:143], v[170:173], v[22:25]
	v_mfma_f32_16x16x32_bf16 v[18:21], v[154:157], v[170:173], v[18:21]
	v_mfma_f32_16x16x32_bf16 v[12:15], v[140:143], v[178:181], v[12:15]
	v_mfma_f32_16x16x32_bf16 v[8:11], v[154:157], v[178:181], v[8:11]
	v_mfma_f32_16x16x32_bf16 v[4:7], v[140:143], v[186:189], v[4:7]
	v_mfma_f32_16x16x32_bf16 v[0:3], v[154:157], v[186:189], v[0:3]
	v_mfma_f32_16x16x32_bf16 v[34:37], v[150:153], v[166:169], v[34:37]
	v_mfma_f32_16x16x32_bf16 v[30:33], v[158:161], v[166:169], v[30:33]
	v_mfma_f32_16x16x32_bf16 v[22:25], v[150:153], v[174:177], v[22:25]
	v_mfma_f32_16x16x32_bf16 v[18:21], v[158:161], v[174:177], v[18:21]
	v_mfma_f32_16x16x32_bf16 v[12:15], v[150:153], v[182:185], v[12:15]
	v_mfma_f32_16x16x32_bf16 v[8:11], v[158:161], v[182:185], v[8:11]
	v_mfma_f32_16x16x32_bf16 v[4:7], v[150:153], v[190:193], v[4:7]
	v_mfma_f32_16x16x32_bf16 v[0:3], v[158:161], v[190:193], v[0:3]
	s_barrier
	s_add_u32 s82, s22, 0x40000
	s_addc_u32 s83, s23, 0
	s_add_i32 s61, s79, s48
	v_lshl_add_u64 v[140:141], s[82:83], 0, v[16:17]
	s_mov_b32 m0, s61
	s_nop 0
	global_load_lds_dwordx4 v[140:141], off
	v_lshl_add_u64 v[140:141], s[82:83], 0, v[130:131]
	s_add_i32 m0, s61, 0x2000
	s_nop 0
	global_load_lds_dwordx4 v[140:141], off
	s_waitcnt vmcnt(10)
	s_barrier
	v_mfma_f32_16x16x32_bf16 v[94:97], v[194:197], v[162:165], v[94:97]
	v_mfma_f32_16x16x32_bf16 v[90:93], v[212:215], v[162:165], v[90:93]
	v_mfma_f32_16x16x32_bf16 v[86:89], v[194:197], v[170:173], v[86:89]
	v_mfma_f32_16x16x32_bf16 v[82:85], v[212:215], v[170:173], v[82:85]
	v_mfma_f32_16x16x32_bf16 v[58:61], v[194:197], v[178:181], v[58:61]
	v_mfma_f32_16x16x32_bf16 v[46:49], v[212:215], v[178:181], v[46:49]
	v_mfma_f32_16x16x32_bf16 v[38:41], v[194:197], v[186:189], v[38:41]
	v_mfma_f32_16x16x32_bf16 v[26:29], v[212:215], v[186:189], v[26:29]
	v_mfma_f32_16x16x32_bf16 v[94:97], v[208:211], v[166:169], v[94:97]
	v_mfma_f32_16x16x32_bf16 v[90:93], v[216:219], v[166:169], v[90:93]
	v_mfma_f32_16x16x32_bf16 v[86:89], v[208:211], v[174:177], v[86:89]
	v_mfma_f32_16x16x32_bf16 v[82:85], v[216:219], v[174:177], v[82:85]
	v_mfma_f32_16x16x32_bf16 v[58:61], v[208:211], v[182:185], v[58:61]
	v_mfma_f32_16x16x32_bf16 v[46:49], v[216:219], v[182:185], v[46:49]
	v_mfma_f32_16x16x32_bf16 v[38:41], v[208:211], v[190:193], v[38:41]
	v_mfma_f32_16x16x32_bf16 v[26:29], v[216:219], v[190:193], v[26:29]
	s_add_i32 s61, 0, 0x18000
	v_add_u32_e32 v158, s61, v147
	s_barrier
	ds_read_b128 v[140:143], v158
	ds_read_b128 v[150:153], v158 offset:1024
	ds_read_b128 v[154:157], v158 offset:2048
	ds_read_b128 v[158:161], v158 offset:3072
	s_add_u32 s28, s28, 0x40000
	s_addc_u32 s29, s29, 0
	s_mov_b32 m0, s49
	v_lshl_add_u64 v[194:195], s[28:29], 0, v[134:135]
	ds_read_b128 v[162:165], v149 offset:32768
	ds_read_b128 v[166:169], v149 offset:33792
	ds_read_b128 v[170:173], v149 offset:34816
	ds_read_b128 v[174:177], v149 offset:35840
	ds_read_b128 v[178:181], v149 offset:36864
	ds_read_b128 v[182:185], v149 offset:37888
	ds_read_b128 v[186:189], v149 offset:38912
	ds_read_b128 v[190:193], v149 offset:39936
	global_load_lds_dwordx4 v[194:195], off
	v_lshl_add_u64 v[194:195], s[28:29], 0, v[132:133]
	s_mov_b32 m0, s50
	s_nop 0
	global_load_lds_dwordx4 v[194:195], off
	s_waitcnt lgkmcnt(8)
	s_waitcnt vmcnt(10)
	s_barrier
	s_waitcnt lgkmcnt(0)
	s_waitcnt lgkmcnt(0)
	v_mfma_f32_16x16x32_bf16 v[78:81], v[140:143], v[162:165], v[78:81]
	v_mfma_f32_16x16x32_bf16 v[74:77], v[154:157], v[162:165], v[74:77]
	v_mfma_f32_16x16x32_bf16 v[70:73], v[140:143], v[170:173], v[70:73]
	v_mfma_f32_16x16x32_bf16 v[66:69], v[154:157], v[170:173], v[66:69]
	v_mfma_f32_16x16x32_bf16 v[62:65], v[140:143], v[178:181], v[62:65]
	v_mfma_f32_16x16x32_bf16 v[54:57], v[154:157], v[178:181], v[54:57]
	v_mfma_f32_16x16x32_bf16 v[50:53], v[140:143], v[186:189], v[50:53]
	v_mfma_f32_16x16x32_bf16 v[42:45], v[154:157], v[186:189], v[42:45]
	v_mfma_f32_16x16x32_bf16 v[78:81], v[150:153], v[166:169], v[78:81]
	v_mfma_f32_16x16x32_bf16 v[74:77], v[158:161], v[166:169], v[74:77]
	v_mfma_f32_16x16x32_bf16 v[70:73], v[150:153], v[174:177], v[70:73]
	v_mfma_f32_16x16x32_bf16 v[66:69], v[158:161], v[174:177], v[66:69]
	v_mfma_f32_16x16x32_bf16 v[62:65], v[150:153], v[182:185], v[62:65]
	v_mfma_f32_16x16x32_bf16 v[54:57], v[158:161], v[182:185], v[54:57]
	v_mfma_f32_16x16x32_bf16 v[50:53], v[150:153], v[190:193], v[50:53]
	v_mfma_f32_16x16x32_bf16 v[42:45], v[158:161], v[190:193], v[42:45]
	s_barrier
	s_add_i32 s28, 0, 0x1c000
	s_add_i32 s29, s61, s48
	v_add_u32_e32 v216, s28, v147
	v_lshl_add_u64 v[144:145], v[144:145], 0, s[10:11]
	s_mov_b32 m0, s29
	ds_read_b128 v[194:197], v216
	ds_read_b128 v[208:211], v216 offset:1024
	ds_read_b128 v[212:215], v216 offset:2048
	ds_read_b128 v[216:219], v216 offset:3072
	global_load_lds_dwordx4 v[144:145], off
	v_lshl_add_u64 v[144:145], v[220:221], 0, s[10:11]
	s_add_i32 m0, s29, 0x2000
	s_nop 0
	global_load_lds_dwordx4 v[144:145], off
	s_waitcnt vmcnt(10)
	s_barrier
	s_waitcnt lgkmcnt(0)
	s_waitcnt lgkmcnt(0)
	v_mfma_f32_16x16x32_bf16 v[126:129], v[194:197], v[162:165], v[126:129]
	v_mfma_f32_16x16x32_bf16 v[122:125], v[212:215], v[162:165], v[122:125]
	v_mfma_f32_16x16x32_bf16 v[118:121], v[194:197], v[170:173], v[118:121]
	v_mfma_f32_16x16x32_bf16 v[114:117], v[212:215], v[170:173], v[114:117]
	v_mfma_f32_16x16x32_bf16 v[110:113], v[194:197], v[178:181], v[110:113]
	v_mfma_f32_16x16x32_bf16 v[106:109], v[212:215], v[178:181], v[106:109]
	v_mfma_f32_16x16x32_bf16 v[102:105], v[194:197], v[186:189], v[102:105]
	v_mfma_f32_16x16x32_bf16 v[98:101], v[212:215], v[186:189], v[98:101]
	v_mfma_f32_16x16x32_bf16 v[126:129], v[208:211], v[166:169], v[126:129]
	v_mfma_f32_16x16x32_bf16 v[122:125], v[216:219], v[166:169], v[122:125]
	v_mfma_f32_16x16x32_bf16 v[118:121], v[208:211], v[174:177], v[118:121]
	v_mfma_f32_16x16x32_bf16 v[114:117], v[216:219], v[174:177], v[114:117]
	v_mfma_f32_16x16x32_bf16 v[110:113], v[208:211], v[182:185], v[110:113]
	v_mfma_f32_16x16x32_bf16 v[106:109], v[216:219], v[182:185], v[106:109]
	v_mfma_f32_16x16x32_bf16 v[102:105], v[208:211], v[190:193], v[102:105]
	v_mfma_f32_16x16x32_bf16 v[98:101], v[216:219], v[190:193], v[98:101]
	s_mov_b32 m0, s51
	v_lshl_add_u64 v[144:145], v[222:223], 0, s[10:11]
	s_barrier
	ds_read_b128 v[162:165], v149 offset:49152
	ds_read_b128 v[166:169], v149 offset:50176
	ds_read_b128 v[170:173], v149 offset:51200
	ds_read_b128 v[174:177], v149 offset:52224
	ds_read_b128 v[178:181], v149 offset:53248
	ds_read_b128 v[182:185], v149 offset:54272
	ds_read_b128 v[186:189], v149 offset:55296
	ds_read_b128 v[190:193], v149 offset:56320
	global_load_lds_dwordx4 v[144:145], off
	v_lshl_add_u64 v[144:145], v[224:225], 0, s[10:11]
	s_mov_b32 m0, s52
	s_nop 0
	global_load_lds_dwordx4 v[144:145], off
	s_barrier
	s_waitcnt lgkmcnt(0)
	s_waitcnt lgkmcnt(0)
	v_mfma_f32_16x16x32_bf16 v[34:37], v[140:143], v[162:165], v[34:37]
	v_mfma_f32_16x16x32_bf16 v[30:33], v[154:157], v[162:165], v[30:33]
	v_mfma_f32_16x16x32_bf16 v[22:25], v[140:143], v[170:173], v[22:25]
	v_mfma_f32_16x16x32_bf16 v[18:21], v[154:157], v[170:173], v[18:21]
	v_mfma_f32_16x16x32_bf16 v[12:15], v[140:143], v[178:181], v[12:15]
	v_mfma_f32_16x16x32_bf16 v[8:11], v[154:157], v[178:181], v[8:11]
	v_mfma_f32_16x16x32_bf16 v[4:7], v[140:143], v[186:189], v[4:7]
	v_mfma_f32_16x16x32_bf16 v[0:3], v[154:157], v[186:189], v[0:3]
	v_mfma_f32_16x16x32_bf16 v[34:37], v[150:153], v[166:169], v[34:37]
	v_mfma_f32_16x16x32_bf16 v[30:33], v[158:161], v[166:169], v[30:33]
	v_mfma_f32_16x16x32_bf16 v[22:25], v[150:153], v[174:177], v[22:25]
	v_mfma_f32_16x16x32_bf16 v[18:21], v[158:161], v[174:177], v[18:21]
	v_mfma_f32_16x16x32_bf16 v[12:15], v[150:153], v[182:185], v[12:15]
	v_mfma_f32_16x16x32_bf16 v[8:11], v[158:161], v[182:185], v[8:11]
	v_mfma_f32_16x16x32_bf16 v[4:7], v[150:153], v[190:193], v[4:7]
	v_mfma_f32_16x16x32_bf16 v[0:3], v[158:161], v[190:193], v[0:3]
	s_barrier
	s_add_u32 s22, s22, 0x40080
	s_addc_u32 s23, s23, 0
	s_add_i32 s28, s28, s48
	v_lshl_add_u64 v[140:141], s[22:23], 0, v[16:17]
	s_mov_b32 m0, s28
	s_nop 0
	global_load_lds_dwordx4 v[140:141], off
	v_lshl_add_u64 v[140:141], s[22:23], 0, v[130:131]
	s_add_i32 m0, s28, 0x2000
	s_nop 0
	global_load_lds_dwordx4 v[140:141], off
	s_cmp_eq_u32 s60, 12
	s_cbranch_scc0 .Lvl_4
	s_waitcnt vmcnt(6)
.Lvl_4:
	s_waitcnt vmcnt(10)
	s_barrier
	v_mfma_f32_16x16x32_bf16 v[94:97], v[194:197], v[162:165], v[94:97]
	v_mfma_f32_16x16x32_bf16 v[90:93], v[212:215], v[162:165], v[90:93]
	v_mfma_f32_16x16x32_bf16 v[86:89], v[194:197], v[170:173], v[86:89]
	v_mfma_f32_16x16x32_bf16 v[82:85], v[212:215], v[170:173], v[82:85]
	v_mfma_f32_16x16x32_bf16 v[58:61], v[194:197], v[178:181], v[58:61]
	v_mfma_f32_16x16x32_bf16 v[46:49], v[212:215], v[178:181], v[46:49]
	v_mfma_f32_16x16x32_bf16 v[38:41], v[194:197], v[186:189], v[38:41]
	v_mfma_f32_16x16x32_bf16 v[26:29], v[212:215], v[186:189], v[26:29]
	v_mfma_f32_16x16x32_bf16 v[94:97], v[208:211], v[166:169], v[94:97]
	v_mfma_f32_16x16x32_bf16 v[90:93], v[216:219], v[166:169], v[90:93]
	v_mfma_f32_16x16x32_bf16 v[86:89], v[208:211], v[174:177], v[86:89]
	v_mfma_f32_16x16x32_bf16 v[82:85], v[216:219], v[174:177], v[82:85]
	v_mfma_f32_16x16x32_bf16 v[58:61], v[208:211], v[182:185], v[58:61]
	v_mfma_f32_16x16x32_bf16 v[46:49], v[216:219], v[182:185], v[46:49]
	v_mfma_f32_16x16x32_bf16 v[38:41], v[208:211], v[190:193], v[38:41]
	v_mfma_f32_16x16x32_bf16 v[26:29], v[216:219], v[190:193], v[26:29]
	s_add_i32 s60, s60, 2
	s_add_u32 s58, s58, 0x100
	s_addc_u32 s59, s59, 0
	s_add_u32 s20, s20, 0x100
	s_addc_u32 s21, s21, 0
	s_cmp_gt_u32 s60, 13
	s_barrier
	s_cbranch_scc0 .LBB0_979
	v_lshl_or_b32 v144, s19, 8, v148
	v_lshl_add_u32 v140, s18, 8, v146
	v_ashrrev_i32_e32 v145, 31, v144
	v_mov_b64_e32 v[142:143], s[94:95]
	v_mad_i64_i32 v[150:151], s[20:21], v140, s66, v[142:143]
	v_lshlrev_b64 v[144:145], 1, v[144:145]
	v_lshl_add_u64 v[154:155], v[150:151], 0, v[144:145]
	v_cvt_pk_bf16_f32 v150, v78, v79
	v_cvt_pk_bf16_f32 v151, v80, v81
	v_cvt_pk_bf16_f32 v152, v74, v75
	v_cvt_pk_bf16_f32 v153, v76, v77
	global_store_dwordx4 v[154:155], v[150:153], off
	v_cvt_pk_bf16_f32 v126, v126, v127
	v_cvt_pk_bf16_f32 v127, v128, v129
	v_cvt_pk_bf16_f32 v128, v122, v123
	v_cvt_pk_bf16_f32 v129, v124, v125
	global_store_dwordx4 v[154:155], v[126:129], off offset:256
	v_or_b32_e32 v122, 16, v140
	v_mad_i64_i32 v[124:125], s[20:21], v122, s66, v[142:143]
	v_lshl_add_u64 v[128:129], v[124:125], 0, v[144:145]
	v_cvt_pk_bf16_f32 v124, v70, v71
	v_cvt_pk_bf16_f32 v125, v72, v73
	v_cvt_pk_bf16_f32 v126, v66, v67
	v_cvt_pk_bf16_f32 v127, v68, v69
	global_store_dwordx4 v[128:129], v[124:127], off
	v_cvt_pk_bf16_f32 v118, v118, v119
	v_cvt_pk_bf16_f32 v119, v120, v121
	v_cvt_pk_bf16_f32 v120, v114, v115
	v_cvt_pk_bf16_f32 v121, v116, v117
	global_store_dwordx4 v[128:129], v[118:121], off offset:256
	v_or_b32_e32 v114, 32, v140
	v_mad_i64_i32 v[116:117], s[20:21], v114, s66, v[142:143]
	v_lshl_add_u64 v[120:121], v[116:117], 0, v[144:145]
	v_cvt_pk_bf16_f32 v116, v62, v63
	v_cvt_pk_bf16_f32 v117, v64, v65
	v_cvt_pk_bf16_f32 v118, v54, v55
	v_cvt_pk_bf16_f32 v119, v56, v57
	global_store_dwordx4 v[120:121], v[116:119], off
	v_cvt_pk_bf16_f32 v110, v110, v111
	v_cvt_pk_bf16_f32 v111, v112, v113
	v_cvt_pk_bf16_f32 v112, v106, v107
	v_cvt_pk_bf16_f32 v113, v108, v109
	global_store_dwordx4 v[120:121], v[110:113], off offset:256
	v_or_b32_e32 v106, 48, v140
	v_mad_i64_i32 v[108:109], s[20:21], v106, s66, v[142:143]
	v_lshl_add_u64 v[112:113], v[108:109], 0, v[144:145]
	v_cvt_pk_bf16_f32 v108, v50, v51
	v_cvt_pk_bf16_f32 v109, v52, v53
	v_cvt_pk_bf16_f32 v110, v42, v43
	v_cvt_pk_bf16_f32 v111, v44, v45
	global_store_dwordx4 v[112:113], v[108:111], off
	v_cvt_pk_bf16_f32 v102, v102, v103
	v_cvt_pk_bf16_f32 v103, v104, v105
	v_cvt_pk_bf16_f32 v104, v98, v99
	v_cvt_pk_bf16_f32 v105, v100, v101
	global_store_dwordx4 v[112:113], v[102:105], off offset:256
	v_add_u32_e32 v98, 0x80, v140
	v_mad_i64_i32 v[100:101], s[20:21], v98, s66, v[142:143]
	v_lshl_add_u64 v[104:105], v[100:101], 0, v[144:145]
	v_cvt_pk_bf16_f32 v100, v34, v35
	v_cvt_pk_bf16_f32 v101, v36, v37
	v_cvt_pk_bf16_f32 v102, v30, v31
	v_cvt_pk_bf16_f32 v103, v32, v33
	global_store_dwordx4 v[104:105], v[100:103], off
	v_cvt_pk_bf16_f32 v94, v94, v95
	v_cvt_pk_bf16_f32 v95, v96, v97
	v_cvt_pk_bf16_f32 v96, v90, v91
	v_cvt_pk_bf16_f32 v97, v92, v93
	global_store_dwordx4 v[104:105], v[94:97], off offset:256
	v_add_u32_e32 v90, 0x90, v140
	v_mad_i64_i32 v[92:93], s[20:21], v90, s66, v[142:143]
	v_lshl_add_u64 v[96:97], v[92:93], 0, v[144:145]
	v_cvt_pk_bf16_f32 v92, v22, v23
	v_cvt_pk_bf16_f32 v93, v24, v25
	v_cvt_pk_bf16_f32 v94, v18, v19
	v_cvt_pk_bf16_f32 v95, v20, v21
	global_store_dwordx4 v[96:97], v[92:95], off
	v_cvt_pk_bf16_f32 v86, v86, v87
	v_cvt_pk_bf16_f32 v87, v88, v89
	v_cvt_pk_bf16_f32 v88, v82, v83
	v_cvt_pk_bf16_f32 v89, v84, v85
	global_store_dwordx4 v[96:97], v[86:89], off offset:256
	v_add_u32_e32 v82, 0xa0, v140
	v_mad_i64_i32 v[84:85], s[20:21], v82, s66, v[142:143]
	v_lshl_add_u64 v[88:89], v[84:85], 0, v[144:145]
	v_cvt_pk_bf16_f32 v84, v12, v13
	v_cvt_pk_bf16_f32 v85, v14, v15
	v_cvt_pk_bf16_f32 v86, v8, v9
	v_cvt_pk_bf16_f32 v87, v10, v11
	global_store_dwordx4 v[88:89], v[84:87], off
	v_cvt_pk_bf16_f32 v58, v58, v59
	v_cvt_pk_bf16_f32 v59, v60, v61
	v_cvt_pk_bf16_f32 v60, v46, v47
	v_cvt_pk_bf16_f32 v61, v48, v49
	global_store_dwordx4 v[88:89], v[58:61], off offset:256
	v_add_u32_e32 v46, 0xb0, v140
	v_mad_i64_i32 v[48:49], s[20:21], v46, s66, v[142:143]
	v_lshl_add_u64 v[48:49], v[48:49], 0, v[144:145]
	v_cvt_pk_bf16_f32 v58, v4, v5
	v_cvt_pk_bf16_f32 v59, v6, v7
	v_cvt_pk_bf16_f32 v60, v0, v1
	v_cvt_pk_bf16_f32 v61, v2, v3
	global_store_dwordx4 v[48:49], v[58:61], off
	v_cvt_pk_bf16_f32 v38, v38, v39
	v_cvt_pk_bf16_f32 v39, v40, v41
	v_cvt_pk_bf16_f32 v40, v26, v27
	v_cvt_pk_bf16_f32 v41, v28, v29
	global_store_dwordx4 v[48:49], v[38:41], off offset:256
	s_cmp_eq_u32 s19, 34
	s_cselect_b64 s[18:19], -1, 0
	s_and_b64 s[20:21], s[38:39], s[18:19]
	s_and_saveexec_b64 s[18:19], s[20:21]
	s_cbranch_execz .LBB0_975
	v_ashrrev_i32_e32 v141, 31, v140
	v_lshlrev_b64 v[26:27], 5, v[140:141]
	v_ashrrev_i32_e32 v123, 31, v122
	v_lshl_add_u64 v[26:27], s[42:43], 0, v[26:27]
	global_store_dwordx4 v[26:27], v[78:81], off
	global_store_dwordx4 v[26:27], v[74:77], off offset:16
	v_lshlrev_b64 v[26:27], 5, v[122:123]
	v_ashrrev_i32_e32 v115, 31, v114
	v_lshl_add_u64 v[26:27], s[42:43], 0, v[26:27]
	global_store_dwordx4 v[26:27], v[70:73], off
	global_store_dwordx4 v[26:27], v[66:69], off offset:16
	v_lshlrev_b64 v[26:27], 5, v[114:115]
	v_ashrrev_i32_e32 v107, 31, v106
	v_lshl_add_u64 v[26:27], s[42:43], 0, v[26:27]
	global_store_dwordx4 v[26:27], v[62:65], off
	global_store_dwordx4 v[26:27], v[54:57], off offset:16
	v_lshlrev_b64 v[26:27], 5, v[106:107]
	v_ashrrev_i32_e32 v99, 31, v98
	v_lshl_add_u64 v[26:27], s[42:43], 0, v[26:27]
	global_store_dwordx4 v[26:27], v[50:53], off
	global_store_dwordx4 v[26:27], v[42:45], off offset:16
	v_lshlrev_b64 v[26:27], 5, v[98:99]
	v_ashrrev_i32_e32 v91, 31, v90
	v_lshl_add_u64 v[26:27], s[42:43], 0, v[26:27]
	global_store_dwordx4 v[26:27], v[34:37], off
	global_store_dwordx4 v[26:27], v[30:33], off offset:16
	v_lshlrev_b64 v[26:27], 5, v[90:91]
	v_ashrrev_i32_e32 v83, 31, v82
	v_lshl_add_u64 v[26:27], s[42:43], 0, v[26:27]
	global_store_dwordx4 v[26:27], v[22:25], off
	global_store_dwordx4 v[26:27], v[18:21], off offset:16
	v_ashrrev_i32_e32 v47, 31, v46
	s_nop 0
	v_lshlrev_b64 v[18:19], 5, v[82:83]
	v_lshl_add_u64 v[18:19], s[42:43], 0, v[18:19]
	global_store_dwordx4 v[18:19], v[12:15], off
	global_store_dwordx4 v[18:19], v[8:11], off offset:16
	s_nop 1
	v_lshlrev_b64 v[8:9], 5, v[46:47]
	v_lshl_add_u64 v[8:9], s[42:43], 0, v[8:9]
	global_store_dwordx4 v[8:9], v[4:7], off
	global_store_dwordx4 v[8:9], v[0:3], off offset:16
	s_branch .LBB0_975
